# cross-attention V^T.P^T chunks 1-7: eight V fragment reads in flight ahead of the MFMA chain (registers dead after softmax) instead of pairs with full LDS waits
# speedup vs baseline: 1.0026x; 1.0026x over previous
; #define XLAS __attribute__((address_space(3)))
; __device__ __forceinline__ void unit(XLAS unsigned char* lds, const bf16_t* Qg, const bf16_t* Kg, const bf16_t* Vg, bf16_t* Og) {
;     int tid_ = threadIdx.x; asm volatile("" : "+v"(tid_)); const int tid = tid_, lane = tid & 63, r32 = lane & 31, hi = lane >> 5; const int wid = __builtin_amdgcn_readfirstlane(tid >> 6);
;     const int sr = tid >> 4, sseg = tid & 15;
;     const bf16_t* kgp = Kg + (size_t)sr * 4096 + sseg * 16;
;     const bf16_t* vgp = Vg + (size_t)sr * 4096 + sseg * 16;
;     const unsigned wofs = (unsigned)(sr * KP + sseg * 32);
;     ...
;     u32x4 g[2][2];
;     g[0][0] = *(const u32x4*)(XAT_SRC(0)); g[0][1] = *(const u32x4*)(XAT_SRC(0) + 8); g[1][0] = *(const u32x4*)(XAT_SRC(1)); g[1][1] = *(const u32x4*)(XAT_SRC(1) + 8);
;     XLAS unsigned char* xs = lds + XS_OFF + wid * XS_BYTES;
;     bf16x8 qf[16];
; #pragma unroll
;     for (int hq = 0; hq < 2; ++hq) {
;         const bf16_t* qbase = Qg + (size_t)(wid * 32 + (lane >> 4)) * 1024 + hq * 128 + (lane & 15) * 8;
;         u32x4 qv[8];
; #pragma unroll
;         for (int i = 0; i < 8; ++i) qv[i] = *(const u32x4*)(qbase + (size_t)(4 * i) * 1024);
; #pragma unroll
;         for (int i = 0; i < 8; ++i) *(XLAS u32x4*)(xs + (4 * i + (lane >> 4)) * 272 + (lane & 15) * 16) = qv[i];
; #pragma unroll
;         for (int s = 0; s < 8; ++s) qf[hq * 8 + s] = *(const XLAS bf16x8*)(xs + r32 * 272 + s * 32 + hi * 16);
;     }
;     const int krow = (r32 & 0x13) | ((r32 & 4) << 1) | ((r32 & 8) >> 1);
;     const unsigned kro = (unsigned)(krow * KP + hi * 16), vro = (unsigned)(r32 * KP + hi * 16);
;     f32x16 S[8];
; #pragma unroll
;     for (int c = 0; c < 8; ++c) {
;         XLAS unsigned char* buf = lds + (c & 1) * CHB;
;         *(XLAS u32x4*)(buf + wofs) = g[c & 1][0]; *(XLAS u32x4*)(buf + wofs + 16) = g[c & 1][1];
;         __syncthreads();
.LBB0_589:
	s_ashr_i32 s67, s66, 31
	s_ashr_i32 s4, s66, 4
	s_lshl_b64 s[26:27], s[66:67], 19
	s_add_u32 s5, s52, s26
	v_readlane_b32 s8, v255, 39
	s_addc_u32 s16, s53, s27
	s_lshl_b32 s8, s8, 8
	s_ashr_i32 s9, s8, 31
	s_lshl_b64 s[28:29], s[8:9], 1
	s_add_u32 s54, s5, s28
	s_addc_u32 s55, s16, s29
	s_ashr_i32 s5, s4, 31
	s_lshl_b64 s[16:17], s[4:5], 21
	s_add_u32 s5, s3, s16
	s_addc_u32 s9, s7, s17
	s_add_u32 s16, s5, s28
	s_addc_u32 s17, s9, s29
	s_add_i32 s8, s8, s6
	s_ashr_i32 s9, s8, 31
	s_lshl_b64 s[8:9], s[8:9], 13
	s_add_u32 s8, s86, s8
	s_addc_u32 s9, s87, s9
	s_lshl_b32 s4, s4, 8
	s_ashr_i32 s5, s4, 31
	s_lshl_b64 s[4:5], s[4:5], 1
	s_add_u32 s8, s8, s4
	s_addc_u32 s9, s9, s5
	s_add_u32 s4, s50, s26
	s_addc_u32 s5, s51, s27
	v_mov_b32_e32 v215, v206
	s_add_u32 s4, s4, s28
	s_addc_u32 s5, s5, s29
	v_readfirstlane_b32 s26, v215
	s_ashr_i32 s27, s26, 6
	s_lshl_b32 s26, s27, 5
	v_bfe_u32 v90, v215, 4, 2
	v_or_b32_e32 v2, s26, v90
	v_ashrrev_i32_e32 v3, 31, v2
	v_and_b32_e32 v80, 15, v215
	v_lshlrev_b64 v[2:3], 11, v[2:3]
	v_lshlrev_b32_e32 v0, 4, v80
	v_lshl_add_u64 v[2:3], s[54:55], 0, v[2:3]
	v_lshl_add_u64 v[6:7], v[2:3], 0, v[0:1]
	v_add_co_u32_e32 v8, vcc, s33, v6
	s_movk_i32 s28, 0x4000
	s_nop 0
	v_addc_co_u32_e32 v9, vcc, 0, v7, vcc
	v_add_co_u32_e32 v10, vcc, s28, v6
	s_mov_b32 s29, 0x8000
	s_nop 0
	v_addc_co_u32_e32 v11, vcc, 0, v7, vcc
	v_add_co_u32_e32 v12, vcc, s2, v6
	s_mov_b32 s42, 0xc000
	s_nop 0
	v_addc_co_u32_e32 v13, vcc, 0, v7, vcc
	v_add_co_u32_e32 v14, vcc, s29, v6
	s_mov_b32 s44, 0xe000
	s_nop 0
	v_addc_co_u32_e32 v15, vcc, 0, v7, vcc
	v_add_co_u32_e32 v16, vcc, s1, v6
	v_ashrrev_i32_e32 v88, 4, v215
	s_nop 0
	v_addc_co_u32_e32 v17, vcc, 0, v7, vcc
	v_add_co_u32_e32 v18, vcc, s42, v6
	v_ashrrev_i32_e32 v89, 31, v88
	s_nop 0
	v_addc_co_u32_e32 v19, vcc, 0, v7, vcc
	v_add_co_u32_e32 v76, vcc, s44, v6
	global_load_dwordx4 v[2:5], v[6:7], off
	global_load_dwordx4 v[20:23], v[8:9], off
	v_addc_co_u32_e32 v77, vcc, 0, v7, vcc
	global_load_dwordx4 v[24:27], v[10:11], off
	global_load_dwordx4 v[28:31], v[12:13], off
	global_load_dwordx4 v[32:35], v[14:15], off
	global_load_dwordx4 v[36:39], v[16:17], off
	global_load_dwordx4 v[40:43], v[18:19], off
	global_load_dwordx4 v[44:47], v[76:77], off
	global_load_dwordx4 v[48:51], v[6:7], off offset:256
	global_load_dwordx4 v[52:55], v[8:9], off offset:256
	global_load_dwordx4 v[56:59], v[10:11], off offset:256
	global_load_dwordx4 v[60:63], v[12:13], off offset:256
	global_load_dwordx4 v[64:67], v[14:15], off offset:256
	global_load_dwordx4 v[68:71], v[16:17], off offset:256
	global_load_dwordx4 v[72:75], v[18:19], off offset:256
	s_nop 0
	global_load_dwordx4 v[76:79], v[76:77], off offset:256
	v_lshlrev_b64 v[16:17], 13, v[88:89]
	v_lshl_add_u64 v[6:7], s[16:17], 0, v[16:17]
	v_lshlrev_b32_e32 v18, 5, v80
	v_mov_b32_e32 v19, v1
	v_lshl_add_u64 v[14:15], v[6:7], 0, v[18:19]
	global_load_dwordx4 v[80:83], v[14:15], off
	global_load_dwordx4 v[84:87], v[14:15], off offset:16
	s_mulk_i32 s27, 0x2200
	v_and_b32_e32 v216, 31, v215
	v_bfe_u32 v217, v215, 5, 1
	v_add_co_u32_e32 v8, vcc, s45, v14
	s_add_i32 s16, s27, 0
	v_mul_u32_u24_e32 v90, 0x110, v90
	v_lshl_add_u64 v[6:7], v[14:15], 0, s[22:23]
	v_addc_co_u32_e32 v9, vcc, 0, v15, vcc
	v_mul_u32_u24_e32 v89, 0x110, v216
	v_lshlrev_b32_e32 v218, 4, v217
	v_add3_u32 v0, s16, v0, v90
	global_load_dwordx4 v[10:13], v[8:9], off
	s_nop 0
	global_load_dwordx4 v[6:9], v[6:7], off offset:16
	v_add3_u32 v89, s16, v89, v218
	s_movk_i32 s17, 0x210
	v_lshl_add_u64 v[16:17], s[8:9], 0, v[16:17]
	v_lshl_add_u64 v[212:213], v[16:17], 0, v[18:19]
	s_waitcnt vmcnt(19)
	ds_write_b128 v0, v[2:5] offset:34816
	s_waitcnt vmcnt(18)
	ds_write_b128 v0, v[20:23] offset:35904
	s_waitcnt vmcnt(17)
	ds_write_b128 v0, v[24:27] offset:36992
	s_waitcnt vmcnt(16)
	ds_write_b128 v0, v[28:31] offset:38080
	s_waitcnt vmcnt(15)
	ds_write_b128 v0, v[32:35] offset:39168
	s_waitcnt vmcnt(14)
	ds_write_b128 v0, v[36:39] offset:40256
	s_waitcnt vmcnt(13)
	ds_write_b128 v0, v[40:43] offset:41344
	s_waitcnt vmcnt(12)
	ds_write_b128 v0, v[44:47] offset:42432
	ds_read_b128 v[2:5], v89 offset:34816
	ds_read_b128 v[170:173], v89 offset:34848
	ds_read_b128 v[166:169], v89 offset:34880
	ds_read_b128 v[162:165], v89 offset:34912
	ds_read_b128 v[158:161], v89 offset:34944
	ds_read_b128 v[154:157], v89 offset:34976
	ds_read_b128 v[134:137], v89 offset:35008
	ds_read_b128 v[130:133], v89 offset:35040
	s_waitcnt vmcnt(11)
	ds_write_b128 v0, v[48:51] offset:34816
	s_waitcnt vmcnt(10)
	ds_write_b128 v0, v[52:55] offset:35904
	s_waitcnt vmcnt(9)
	ds_write_b128 v0, v[56:59] offset:36992
	s_waitcnt vmcnt(8)
	ds_write_b128 v0, v[60:63] offset:38080
	s_waitcnt vmcnt(7)
	ds_write_b128 v0, v[64:67] offset:39168
	s_waitcnt vmcnt(6)
	ds_write_b128 v0, v[68:71] offset:40256
	s_waitcnt vmcnt(5)
	ds_write_b128 v0, v[72:75] offset:41344
	s_waitcnt vmcnt(4)
	ds_write_b128 v0, v[76:79] offset:42432
	v_mul_lo_u32 v0, v88, s17
	v_add_co_u32_e32 v22, vcc, s46, v14
	v_add3_u32 v214, v0, v18, 0
	s_nop 0
	v_addc_co_u32_e32 v23, vcc, 0, v15, vcc
	ds_read_b128 v[202:205], v89 offset:34816
	ds_read_b128 v[198:201], v89 offset:34848
	ds_read_b128 v[194:197], v89 offset:34880
	ds_read_b128 v[190:193], v89 offset:34912
	ds_read_b128 v[186:189], v89 offset:34944
	ds_read_b128 v[182:185], v89 offset:34976
	ds_read_b128 v[178:181], v89 offset:35008
	ds_read_b128 v[174:177], v89 offset:35040
	s_waitcnt vmcnt(3)
	ds_write_b128 v214, v[80:83]
	s_waitcnt vmcnt(2)
	ds_write_b128 v214, v[84:87] offset:16
	s_waitcnt lgkmcnt(0)
	s_barrier
; #define XLAS __attribute__((address_space(3)))
; __device__ __forceinline__ void unit(XLAS unsigned char* lds, const bf16_t* Qg, const bf16_t* Kg, const bf16_t* Vg, bf16_t* Og) {
;     ...
;     for (int c = 0; c < 8; ++c) {
;         XLAS unsigned char* buf = lds + (c & 1) * CHB;
;         *(XLAS u32x4*)(buf + wofs) = g[c & 1][0]; *(XLAS u32x4*)(buf + wofs + 16) = g[c & 1][1];
;         __syncthreads();
;         { g[c & 1][0] = *(const u32x4*)(XAT_SRC(c + 2)); g[c & 1][1] = *(const u32x4*)(XAT_SRC(c + 2) + 8); }
;         f32x16 a = {};
;         bf16x8 kfa[4], kfb[4];
; #pragma unroll
;         for (int j = 0; j < 4; ++j) kfa[j] = *(const XLAS bf16x8*)(buf + kro + j * 32);
; #pragma unroll
;         for (int gq = 0; gq < 4; gq += 2) {
; #pragma unroll
;             for (int j = 0; j < 4; ++j) kfb[j] = *(const XLAS bf16x8*)(buf + kro + (4 * gq + 4 + j) * 32);
;             __builtin_amdgcn_sched_barrier(0);
; #pragma unroll
;             for (int j = 0; j < 4; ++j) a = __builtin_amdgcn_mfma_f32_32x32x16_bf16(kfa[j], qf[4 * gq + j], a, 0, 0, 0);
;             if (gq < 2) {
; #pragma unroll
;                 for (int j = 0; j < 4; ++j) kfa[j] = *(const XLAS bf16x8*)(buf + kro + (4 * gq + 8 + j) * 32); }
;             __builtin_amdgcn_sched_barrier(0);
; #pragma unroll
;             for (int j = 0; j < 4; ++j) a = __builtin_amdgcn_mfma_f32_32x32x16_bf16(kfb[j], qf[4 * gq + 4 + j], a, 0, 0, 0);
;         }
;         S[c] = a;
;     }
	v_lshl_add_u64 v[20:21], v[14:15], 0, s[34:35]
	global_load_dwordx4 v[50:53], v[22:23], off
	global_load_dwordx4 v[54:57], v[20:21], off offset:16
	v_lshlrev_b32_e32 v20, 1, v215
	v_lshrrev_b32_e32 v21, 1, v215
	v_and_b32_e32 v0, 19, v215
	v_and_b32_e32 v20, 8, v20
	v_and_b32_e32 v21, 4, v21
	v_or3_b32 v0, v0, v20, v21
	v_mul_u32_u24_e32 v0, 0x210, v0
	v_add3_u32 v0, v0, v218, 0
	ds_read_b128 v[20:23], v0
	ds_read_b128 v[34:37], v0 offset:32
	ds_read_b128 v[38:41], v0 offset:64
	ds_read_b128 v[42:45], v0 offset:96
	ds_read_b128 v[46:49], v0 offset:128
	ds_read_b128 v[58:61], v0 offset:160
	ds_read_b128 v[62:65], v0 offset:192
	ds_read_b128 v[66:69], v0 offset:224
	s_waitcnt lgkmcnt(7)
	v_mfma_f32_32x32x16_bf16 v[18:33], v[20:23], v[2:5], 0
	s_waitcnt lgkmcnt(6)
	v_mfma_f32_32x32x16_bf16 v[18:33], v[34:37], v[170:173], v[18:33]
	s_waitcnt lgkmcnt(5)
	v_mfma_f32_32x32x16_bf16 v[18:33], v[38:41], v[166:169], v[18:33]
	ds_read_b128 v[34:37], v0 offset:352
	ds_read_b128 v[38:41], v0 offset:320
	ds_read_b128 v[70:73], v0 offset:256
	ds_read_b128 v[74:77], v0 offset:288
	s_waitcnt lgkmcnt(8)
	v_mfma_f32_32x32x16_bf16 v[18:33], v[42:45], v[162:165], v[18:33]
	s_waitcnt lgkmcnt(7)
	v_mfma_f32_32x32x16_bf16 v[18:33], v[46:49], v[158:161], v[18:33]
	s_waitcnt lgkmcnt(6)
	v_mfma_f32_32x32x16_bf16 v[18:33], v[58:61], v[154:157], v[18:33]
	s_waitcnt lgkmcnt(5)
	v_mfma_f32_32x32x16_bf16 v[18:33], v[62:65], v[134:137], v[18:33]
	ds_read_b128 v[42:45], v0 offset:384
	ds_read_b128 v[46:49], v0 offset:416
	ds_read_b128 v[58:61], v0 offset:448
	ds_read_b128 v[62:65], v0 offset:480
	s_waitcnt lgkmcnt(8)
	v_mfma_f32_32x32x16_bf16 v[18:33], v[66:69], v[130:133], v[18:33]
	s_waitcnt lgkmcnt(5)
	v_mfma_f32_32x32x16_bf16 v[18:33], v[70:73], v[202:205], v[18:33]
	s_waitcnt lgkmcnt(4)
	v_mfma_f32_32x32x16_bf16 v[18:33], v[74:77], v[198:201], v[18:33]
	v_mfma_f32_32x32x16_bf16 v[18:33], v[38:41], v[194:197], v[18:33]
	v_mfma_f32_32x32x16_bf16 v[18:33], v[34:37], v[190:193], v[18:33]
	s_waitcnt vmcnt(3)
	ds_write_b128 v214, v[10:13] offset:16896
	s_waitcnt vmcnt(2)
	ds_write_b128 v214, v[6:9] offset:16912
	v_add_co_u32_e32 v6, vcc, s47, v14
	v_lshl_add_u64 v[10:11], v[14:15], 0, s[36:37]
	s_nop 0
	v_addc_co_u32_e32 v7, vcc, 0, v15, vcc
	s_waitcnt lgkmcnt(0)
	s_barrier
	global_load_dwordx4 v[6:9], v[6:7], off
	s_nop 0
	global_load_dwordx4 v[10:13], v[10:11], off offset:16
	v_mfma_f32_32x32x16_bf16 v[18:33], v[42:45], v[186:189], v[18:33]
	v_mfma_f32_32x32x16_bf16 v[18:33], v[46:49], v[182:185], v[18:33]
	v_mfma_f32_32x32x16_bf16 v[18:33], v[58:61], v[178:181], v[18:33]
	ds_read_b128 v[34:37], v0 offset:16896
	ds_read_b128 v[58:61], v0 offset:16928
	ds_read_b128 v[66:69], v0 offset:16960
	ds_read_b128 v[70:73], v0 offset:16992
	ds_read_b128 v[74:77], v0 offset:17024
	ds_read_b128 v[78:81], v0 offset:17056
	ds_read_b128 v[82:85], v0 offset:17088
	ds_read_b128 v[86:89], v0 offset:17120
	v_mfma_f32_32x32x16_bf16 v[18:33], v[62:65], v[174:177], v[18:33]
	s_waitcnt lgkmcnt(7)
	v_mfma_f32_32x32x16_bf16 v[34:49], v[34:37], v[2:5], 0
	s_waitcnt lgkmcnt(6)
	v_mfma_f32_32x32x16_bf16 v[34:49], v[58:61], v[170:173], v[34:49]
	s_waitcnt lgkmcnt(5)
	v_mfma_f32_32x32x16_bf16 v[34:49], v[66:69], v[166:169], v[34:49]
	ds_read_b128 v[58:61], v0 offset:17248
	ds_read_b128 v[62:65], v0 offset:17216
	ds_read_b128 v[66:69], v0 offset:17152
	ds_read_b128 v[90:93], v0 offset:17184
	s_waitcnt lgkmcnt(8)
	v_mfma_f32_32x32x16_bf16 v[34:49], v[70:73], v[162:165], v[34:49]
	s_waitcnt lgkmcnt(7)
	v_mfma_f32_32x32x16_bf16 v[34:49], v[74:77], v[158:161], v[34:49]
	s_waitcnt lgkmcnt(6)
	v_mfma_f32_32x32x16_bf16 v[34:49], v[78:81], v[154:157], v[34:49]
	s_waitcnt lgkmcnt(5)
	v_mfma_f32_32x32x16_bf16 v[34:49], v[82:85], v[134:137], v[34:49]
	ds_read_b128 v[70:73], v0 offset:17280
	ds_read_b128 v[74:77], v0 offset:17312
	ds_read_b128 v[78:81], v0 offset:17344
	ds_read_b128 v[82:85], v0 offset:17376
	s_waitcnt lgkmcnt(8)
	v_mfma_f32_32x32x16_bf16 v[34:49], v[86:89], v[130:133], v[34:49]
	s_waitcnt lgkmcnt(5)
	v_mfma_f32_32x32x16_bf16 v[34:49], v[66:69], v[202:205], v[34:49]
	s_waitcnt lgkmcnt(4)
	v_mfma_f32_32x32x16_bf16 v[34:49], v[90:93], v[198:201], v[34:49]
	v_mfma_f32_32x32x16_bf16 v[34:49], v[62:65], v[194:197], v[34:49]
	v_mfma_f32_32x32x16_bf16 v[34:49], v[58:61], v[190:193], v[34:49]
	s_mov_b32 s17, 0x100000
	s_waitcnt vmcnt(3)
	ds_write_b128 v214, v[50:53]
	s_waitcnt vmcnt(2)
	ds_write_b128 v214, v[54:57] offset:16
	v_add_co_u32_e32 v50, vcc, s17, v14
	s_waitcnt lgkmcnt(0)
	s_nop 0
	v_addc_co_u32_e32 v51, vcc, 0, v15, vcc
	s_barrier
; #define XLAS __attribute__((address_space(3)))
; __device__ __forceinline__ void unit(XLAS unsigned char* lds, const bf16_t* Qg, const bf16_t* Kg, const bf16_t* Vg, bf16_t* Og) {
;     ...
;     for (int c = 0; c < 8; ++c) {
;         XLAS unsigned char* buf = lds + (c & 1) * CHB;
;         *(XLAS u32x4*)(buf + wofs) = g[c & 1][0]; *(XLAS u32x4*)(buf + wofs + 16) = g[c & 1][1];
;         __syncthreads();
;         { g[c & 1][0] = *(const u32x4*)(XAT_SRC(c + 2)); g[c & 1][1] = *(const u32x4*)(XAT_SRC(c + 2) + 8); }
;         f32x16 a = {};
;         bf16x8 kfa[4], kfb[4];
; #pragma unroll
;         for (int j = 0; j < 4; ++j) kfa[j] = *(const XLAS bf16x8*)(buf + kro + j * 32);
; #pragma unroll
;         for (int gq = 0; gq < 4; gq += 2) {
; #pragma unroll
;             for (int j = 0; j < 4; ++j) kfb[j] = *(const XLAS bf16x8*)(buf + kro + (4 * gq + 4 + j) * 32);
;             __builtin_amdgcn_sched_barrier(0);
; #pragma unroll
;             for (int j = 0; j < 4; ++j) a = __builtin_amdgcn_mfma_f32_32x32x16_bf16(kfa[j], qf[4 * gq + j], a, 0, 0, 0);
;             if (gq < 2) {
; #pragma unroll
;                 for (int j = 0; j < 4; ++j) kfa[j] = *(const XLAS bf16x8*)(buf + kro + (4 * gq + 8 + j) * 32); }
;             __builtin_amdgcn_sched_barrier(0);
; #pragma unroll
;             for (int j = 0; j < 4; ++j) a = __builtin_amdgcn_mfma_f32_32x32x16_bf16(kfb[j], qf[4 * gq + 4 + j], a, 0, 0, 0);
;         }
;         S[c] = a;
;     }
	v_lshl_add_u64 v[16:17], v[14:15], 0, s[30:31]
	global_load_dwordx4 v[86:89], v[50:51], off
	global_load_dwordx4 v[90:93], v[16:17], off offset:16
	v_mfma_f32_32x32x16_bf16 v[34:49], v[70:73], v[186:189], v[34:49]
	v_mfma_f32_32x32x16_bf16 v[34:49], v[74:77], v[182:185], v[34:49]
	v_mfma_f32_32x32x16_bf16 v[34:49], v[78:81], v[178:181], v[34:49]
	ds_read_b128 v[50:53], v0
	ds_read_b128 v[66:69], v0 offset:32
	ds_read_b128 v[70:73], v0 offset:64
	ds_read_b128 v[74:77], v0 offset:96
	ds_read_b128 v[78:81], v0 offset:128
	ds_read_b128 v[94:97], v0 offset:160
	ds_read_b128 v[98:101], v0 offset:192
	ds_read_b128 v[102:105], v0 offset:224
	v_mfma_f32_32x32x16_bf16 v[34:49], v[82:85], v[174:177], v[34:49]
	s_waitcnt lgkmcnt(7)
	v_mfma_f32_32x32x16_bf16 v[50:65], v[50:53], v[2:5], 0
	s_waitcnt lgkmcnt(6)
	v_mfma_f32_32x32x16_bf16 v[50:65], v[66:69], v[170:173], v[50:65]
	s_waitcnt lgkmcnt(5)
	v_mfma_f32_32x32x16_bf16 v[50:65], v[70:73], v[166:169], v[50:65]
	ds_read_b128 v[66:69], v0 offset:352
	ds_read_b128 v[70:73], v0 offset:320
	ds_read_b128 v[82:85], v0 offset:256
	ds_read_b128 v[106:109], v0 offset:288
	s_waitcnt lgkmcnt(8)
	v_mfma_f32_32x32x16_bf16 v[50:65], v[74:77], v[162:165], v[50:65]
	s_waitcnt lgkmcnt(7)
	v_mfma_f32_32x32x16_bf16 v[50:65], v[78:81], v[158:161], v[50:65]
	s_waitcnt lgkmcnt(6)
	v_mfma_f32_32x32x16_bf16 v[50:65], v[94:97], v[154:157], v[50:65]
	s_waitcnt lgkmcnt(5)
	v_mfma_f32_32x32x16_bf16 v[50:65], v[98:101], v[134:137], v[50:65]
	ds_read_b128 v[74:77], v0 offset:384
	ds_read_b128 v[78:81], v0 offset:416
	ds_read_b128 v[94:97], v0 offset:448
	ds_read_b128 v[98:101], v0 offset:480
	s_waitcnt lgkmcnt(8)
	v_mfma_f32_32x32x16_bf16 v[50:65], v[102:105], v[130:133], v[50:65]
	s_waitcnt lgkmcnt(5)
	v_mfma_f32_32x32x16_bf16 v[50:65], v[82:85], v[202:205], v[50:65]
	s_waitcnt lgkmcnt(4)
	v_mfma_f32_32x32x16_bf16 v[50:65], v[106:109], v[198:201], v[50:65]
	v_mfma_f32_32x32x16_bf16 v[50:65], v[70:73], v[194:197], v[50:65]
	v_mfma_f32_32x32x16_bf16 v[50:65], v[66:69], v[190:193], v[50:65]
	s_mov_b32 s27, 0x140000
	s_waitcnt vmcnt(3)
	ds_write_b128 v214, v[6:9] offset:16896
	s_waitcnt vmcnt(2)
	ds_write_b128 v214, v[10:13] offset:16912
	v_add_co_u32_e32 v6, vcc, s27, v14
	v_lshl_add_u64 v[10:11], v[14:15], 0, s[38:39]
	s_nop 0
	v_addc_co_u32_e32 v7, vcc, 0, v15, vcc
	s_waitcnt lgkmcnt(0)
	s_barrier
	global_load_dwordx4 v[6:9], v[6:7], off
	s_nop 0
	global_load_dwordx4 v[10:13], v[10:11], off offset:16
	v_mfma_f32_32x32x16_bf16 v[50:65], v[74:77], v[186:189], v[50:65]
	v_mfma_f32_32x32x16_bf16 v[50:65], v[78:81], v[182:185], v[50:65]
	v_mfma_f32_32x32x16_bf16 v[50:65], v[94:97], v[178:181], v[50:65]
	ds_read_b128 v[66:69], v0 offset:16896
	ds_read_b128 v[82:85], v0 offset:16928
	ds_read_b128 v[94:97], v0 offset:16960
	ds_read_b128 v[102:105], v0 offset:16992
	ds_read_b128 v[106:109], v0 offset:17024
	ds_read_b128 v[110:113], v0 offset:17056
	ds_read_b128 v[114:117], v0 offset:17088
	ds_read_b128 v[118:121], v0 offset:17120
	v_mfma_f32_32x32x16_bf16 v[50:65], v[98:101], v[174:177], v[50:65]
	s_waitcnt lgkmcnt(7)
	v_mfma_f32_32x32x16_bf16 v[66:81], v[66:69], v[2:5], 0
	s_waitcnt lgkmcnt(6)
	v_mfma_f32_32x32x16_bf16 v[66:81], v[82:85], v[170:173], v[66:81]
	s_waitcnt lgkmcnt(5)
	v_mfma_f32_32x32x16_bf16 v[66:81], v[94:97], v[166:169], v[66:81]
	ds_read_b128 v[82:85], v0 offset:17248
	ds_read_b128 v[94:97], v0 offset:17216
	ds_read_b128 v[98:101], v0 offset:17152
	ds_read_b128 v[122:125], v0 offset:17184
	s_waitcnt lgkmcnt(8)
	v_mfma_f32_32x32x16_bf16 v[66:81], v[102:105], v[162:165], v[66:81]
	s_waitcnt lgkmcnt(7)
	v_mfma_f32_32x32x16_bf16 v[66:81], v[106:109], v[158:161], v[66:81]
	s_waitcnt lgkmcnt(6)
	v_mfma_f32_32x32x16_bf16 v[66:81], v[110:113], v[154:157], v[66:81]
	s_waitcnt lgkmcnt(5)
	v_mfma_f32_32x32x16_bf16 v[66:81], v[114:117], v[134:137], v[66:81]
	ds_read_b128 v[102:105], v0 offset:17280
	ds_read_b128 v[106:109], v0 offset:17312
	ds_read_b128 v[110:113], v0 offset:17344
	ds_read_b128 v[114:117], v0 offset:17376
	s_waitcnt lgkmcnt(8)
	v_mfma_f32_32x32x16_bf16 v[66:81], v[118:121], v[130:133], v[66:81]
	s_waitcnt lgkmcnt(5)
	v_mfma_f32_32x32x16_bf16 v[66:81], v[98:101], v[202:205], v[66:81]
	s_waitcnt lgkmcnt(4)
	v_mfma_f32_32x32x16_bf16 v[66:81], v[122:125], v[198:201], v[66:81]
	v_mfma_f32_32x32x16_bf16 v[66:81], v[94:97], v[194:197], v[66:81]
	v_mfma_f32_32x32x16_bf16 v[66:81], v[82:85], v[190:193], v[66:81]
	v_add_co_u32_e32 v82, vcc, s58, v14
	s_waitcnt vmcnt(3)
	ds_write_b128 v214, v[86:89]
	s_waitcnt vmcnt(2)
	ds_write_b128 v214, v[90:93] offset:16
	v_addc_co_u32_e32 v83, vcc, 0, v15, vcc
	s_waitcnt lgkmcnt(0)
	s_barrier
; #define XLAS __attribute__((address_space(3)))
; __device__ __forceinline__ void unit(XLAS unsigned char* lds, const bf16_t* Qg, const bf16_t* Kg, const bf16_t* Vg, bf16_t* Og) {
;     ...
;     for (int c = 0; c < 8; ++c) {
;         XLAS unsigned char* buf = lds + (c & 1) * CHB;
;         *(XLAS u32x4*)(buf + wofs) = g[c & 1][0]; *(XLAS u32x4*)(buf + wofs + 16) = g[c & 1][1];
;         __syncthreads();
;         { g[c & 1][0] = *(const u32x4*)(XAT_SRC(c + 2)); g[c & 1][1] = *(const u32x4*)(XAT_SRC(c + 2) + 8); }
;         f32x16 a = {};
;         bf16x8 kfa[4], kfb[4];
; #pragma unroll
;         for (int j = 0; j < 4; ++j) kfa[j] = *(const XLAS bf16x8*)(buf + kro + j * 32);
; #pragma unroll
;         for (int gq = 0; gq < 4; gq += 2) {
; #pragma unroll
;             for (int j = 0; j < 4; ++j) kfb[j] = *(const XLAS bf16x8*)(buf + kro + (4 * gq + 4 + j) * 32);
;             __builtin_amdgcn_sched_barrier(0);
; #pragma unroll
;             for (int j = 0; j < 4; ++j) a = __builtin_amdgcn_mfma_f32_32x32x16_bf16(kfa[j], qf[4 * gq + j], a, 0, 0, 0);
;             if (gq < 2) {
; #pragma unroll
;                 for (int j = 0; j < 4; ++j) kfa[j] = *(const XLAS bf16x8*)(buf + kro + (4 * gq + 8 + j) * 32); }
;             __builtin_amdgcn_sched_barrier(0);
; #pragma unroll
;             for (int j = 0; j < 4; ++j) a = __builtin_amdgcn_mfma_f32_32x32x16_bf16(kfb[j], qf[4 * gq + 4 + j], a, 0, 0, 0);
;         }
;         S[c] = a;
;     }
	v_lshl_add_u64 v[16:17], v[14:15], 0, s[56:57]
	global_load_dwordx4 v[118:121], v[82:83], off
	global_load_dwordx4 v[122:125], v[16:17], off offset:16
	v_mfma_f32_32x32x16_bf16 v[66:81], v[102:105], v[186:189], v[66:81]
	v_mfma_f32_32x32x16_bf16 v[66:81], v[106:109], v[182:185], v[66:81]
	v_mfma_f32_32x32x16_bf16 v[66:81], v[110:113], v[178:181], v[66:81]
	ds_read_b128 v[82:85], v0
	ds_read_b128 v[98:101], v0 offset:32
	ds_read_b128 v[102:105], v0 offset:64
	ds_read_b128 v[106:109], v0 offset:96
	ds_read_b128 v[110:113], v0 offset:128
	ds_read_b128 v[126:129], v0 offset:160
	ds_read_b128 v[138:141], v0 offset:192
	ds_read_b128 v[142:145], v0 offset:224
	v_mfma_f32_32x32x16_bf16 v[66:81], v[114:117], v[174:177], v[66:81]
	s_waitcnt lgkmcnt(7)
	v_mfma_f32_32x32x16_bf16 v[82:97], v[82:85], v[2:5], 0
	s_waitcnt lgkmcnt(6)
	v_mfma_f32_32x32x16_bf16 v[82:97], v[98:101], v[170:173], v[82:97]
	s_waitcnt lgkmcnt(5)
	v_mfma_f32_32x32x16_bf16 v[82:97], v[102:105], v[166:169], v[82:97]
	ds_read_b128 v[98:101], v0 offset:352
	ds_read_b128 v[102:105], v0 offset:320
	ds_read_b128 v[114:117], v0 offset:256
	ds_read_b128 v[146:149], v0 offset:288
	s_waitcnt lgkmcnt(8)
	v_mfma_f32_32x32x16_bf16 v[82:97], v[106:109], v[162:165], v[82:97]
	s_waitcnt lgkmcnt(7)
	v_mfma_f32_32x32x16_bf16 v[82:97], v[110:113], v[158:161], v[82:97]
	s_waitcnt lgkmcnt(6)
	v_mfma_f32_32x32x16_bf16 v[82:97], v[126:129], v[154:157], v[82:97]
	s_waitcnt lgkmcnt(5)
	v_mfma_f32_32x32x16_bf16 v[82:97], v[138:141], v[134:137], v[82:97]
	ds_read_b128 v[106:109], v0 offset:384
	ds_read_b128 v[110:113], v0 offset:416
	ds_read_b128 v[126:129], v0 offset:448
	ds_read_b128 v[138:141], v0 offset:480
	s_waitcnt lgkmcnt(8)
	v_mfma_f32_32x32x16_bf16 v[82:97], v[142:145], v[130:133], v[82:97]
	s_waitcnt lgkmcnt(5)
	v_mfma_f32_32x32x16_bf16 v[82:97], v[114:117], v[202:205], v[82:97]
	s_waitcnt lgkmcnt(4)
	v_mfma_f32_32x32x16_bf16 v[82:97], v[146:149], v[198:201], v[82:97]
	v_mfma_f32_32x32x16_bf16 v[82:97], v[102:105], v[194:197], v[82:97]
	v_mfma_f32_32x32x16_bf16 v[82:97], v[98:101], v[190:193], v[82:97]
	s_waitcnt vmcnt(3)
	ds_write_b128 v214, v[6:9] offset:16896
	s_waitcnt vmcnt(2)
	ds_write_b128 v214, v[10:13] offset:16912
	v_add_co_u32_e32 v6, vcc, s59, v14
	v_lshl_add_u64 v[10:11], v[14:15], 0, s[60:61]
	s_nop 0
	v_addc_co_u32_e32 v7, vcc, 0, v15, vcc
	s_waitcnt lgkmcnt(0)
	s_barrier
	global_load_dwordx4 v[6:9], v[6:7], off
	s_nop 0
	global_load_dwordx4 v[10:13], v[10:11], off offset:16
	v_mfma_f32_32x32x16_bf16 v[82:97], v[106:109], v[186:189], v[82:97]
	v_mfma_f32_32x32x16_bf16 v[82:97], v[110:113], v[182:185], v[82:97]
	v_mfma_f32_32x32x16_bf16 v[82:97], v[126:129], v[178:181], v[82:97]
	ds_read_b128 v[14:17], v0 offset:16896
	ds_read_b128 v[114:117], v0 offset:16928
	ds_read_b128 v[126:129], v0 offset:16960
	ds_read_b128 v[142:145], v0 offset:16992
	ds_read_b128 v[146:149], v0 offset:17024
	ds_read_b128 v[150:153], v0 offset:17056
	ds_read_b128 v[220:223], v0 offset:17088
	ds_read_b128 v[224:227], v0 offset:17120
	v_mfma_f32_32x32x16_bf16 v[82:97], v[138:141], v[174:177], v[82:97]
	s_waitcnt lgkmcnt(7)
	v_mfma_f32_32x32x16_bf16 v[98:113], v[14:17], v[2:5], 0
	s_waitcnt lgkmcnt(6)
	v_mfma_f32_32x32x16_bf16 v[98:113], v[114:117], v[170:173], v[98:113]
	s_waitcnt lgkmcnt(5)
	v_mfma_f32_32x32x16_bf16 v[98:113], v[126:129], v[166:169], v[98:113]
	ds_read_b128 v[14:17], v0 offset:17248
	ds_read_b128 v[114:117], v0 offset:17216
	ds_read_b128 v[126:129], v0 offset:17152
	ds_read_b128 v[138:141], v0 offset:17184
	s_waitcnt lgkmcnt(8)
	v_mfma_f32_32x32x16_bf16 v[98:113], v[142:145], v[162:165], v[98:113]
	s_waitcnt lgkmcnt(7)
	v_mfma_f32_32x32x16_bf16 v[98:113], v[146:149], v[158:161], v[98:113]
	s_waitcnt lgkmcnt(6)
	v_mfma_f32_32x32x16_bf16 v[98:113], v[150:153], v[154:157], v[98:113]
	s_waitcnt lgkmcnt(5)
	v_mfma_f32_32x32x16_bf16 v[98:113], v[220:223], v[134:137], v[98:113]
	ds_read_b128 v[142:145], v0 offset:17280
	ds_read_b128 v[146:149], v0 offset:17312
	ds_read_b128 v[220:223], v0 offset:17344
	ds_read_b128 v[228:231], v0 offset:17376
	s_waitcnt lgkmcnt(8)
	v_mfma_f32_32x32x16_bf16 v[98:113], v[224:227], v[130:133], v[98:113]
	s_waitcnt lgkmcnt(5)
	v_mfma_f32_32x32x16_bf16 v[98:113], v[126:129], v[202:205], v[98:113]
	s_waitcnt lgkmcnt(4)
	v_mfma_f32_32x32x16_bf16 v[98:113], v[138:141], v[198:201], v[98:113]
	v_mfma_f32_32x32x16_bf16 v[98:113], v[114:117], v[194:197], v[98:113]
	v_mfma_f32_32x32x16_bf16 v[98:113], v[14:17], v[190:193], v[98:113]
	s_waitcnt lgkmcnt(3)
	v_mfma_f32_32x32x16_bf16 v[98:113], v[142:145], v[186:189], v[98:113]
	s_waitcnt vmcnt(3)
	ds_write_b128 v214, v[118:121]
	s_waitcnt vmcnt(2)
	ds_write_b128 v214, v[122:125] offset:16
	s_waitcnt lgkmcnt(0)
	s_barrier
; #define XLAS __attribute__((address_space(3)))
; __device__ __forceinline__ void unit(XLAS unsigned char* lds, const bf16_t* Qg, const bf16_t* Kg, const bf16_t* Vg, bf16_t* Og) {
;     ...
;     for (int c = 0; c < 8; ++c) {
;         XLAS unsigned char* buf = lds + (c & 1) * CHB;
;         *(XLAS u32x4*)(buf + wofs) = g[c & 1][0]; *(XLAS u32x4*)(buf + wofs + 16) = g[c & 1][1];
;         __syncthreads();
;         { g[c & 1][0] = *(const u32x4*)(XAT_SRC(c + 2)); g[c & 1][1] = *(const u32x4*)(XAT_SRC(c + 2) + 8); }
;         f32x16 a = {};
;         bf16x8 kfa[4], kfb[4];
; #pragma unroll
;         for (int j = 0; j < 4; ++j) kfa[j] = *(const XLAS bf16x8*)(buf + kro + j * 32);
; #pragma unroll
;         for (int gq = 0; gq < 4; gq += 2) {
; #pragma unroll
;             for (int j = 0; j < 4; ++j) kfb[j] = *(const XLAS bf16x8*)(buf + kro + (4 * gq + 4 + j) * 32);
;             __builtin_amdgcn_sched_barrier(0);
; #pragma unroll
;             for (int j = 0; j < 4; ++j) a = __builtin_amdgcn_mfma_f32_32x32x16_bf16(kfa[j], qf[4 * gq + j], a, 0, 0, 0);
;             if (gq < 2) {
; #pragma unroll
;                 for (int j = 0; j < 4; ++j) kfa[j] = *(const XLAS bf16x8*)(buf + kro + (4 * gq + 8 + j) * 32); }
;             __builtin_amdgcn_sched_barrier(0);
; #pragma unroll
;             for (int j = 0; j < 4; ++j) a = __builtin_amdgcn_mfma_f32_32x32x16_bf16(kfb[j], qf[4 * gq + 4 + j], a, 0, 0, 0);
;         }
;         S[c] = a;
;     }
;     float mx = S[0][0];
; #pragma unroll
;     for (int c = 0; c < 8; ++c)
; #pragma unroll
;         for (int r = 0; r < 16; ++r) mx = __builtin_fmaxf(mx, S[c][r]);
;     mx = __builtin_fmaxf(mx, __shfl_xor(mx, 32));
	v_mfma_f32_32x32x16_bf16 v[98:113], v[146:149], v[182:185], v[98:113]
	global_load_dwordx4 v[146:149], v[212:213], off offset:16
	global_load_dwordx4 v[150:153], v[212:213], off
	v_mfma_f32_32x32x16_bf16 v[98:113], v[220:223], v[178:181], v[98:113]
	ds_read_b128 v[14:17], v0
	ds_read_b128 v[138:141], v0 offset:32
	ds_read_b128 v[142:145], v0 offset:64
	ds_read_b128 v[220:223], v0 offset:96
	ds_read_b128 v[224:227], v0 offset:128
	ds_read_b128 v[232:235], v0 offset:160
	ds_read_b128 v[236:239], v0 offset:192
	ds_read_b128 v[240:243], v0 offset:224
	v_mfma_f32_32x32x16_bf16 v[98:113], v[228:231], v[174:177], v[98:113]
	s_waitcnt lgkmcnt(7)
	v_mfma_f32_32x32x16_bf16 v[114:129], v[14:17], v[2:5], 0
	s_waitcnt lgkmcnt(6)
	v_mfma_f32_32x32x16_bf16 v[114:129], v[138:141], v[170:173], v[114:129]
	s_waitcnt lgkmcnt(5)
	v_mfma_f32_32x32x16_bf16 v[114:129], v[142:145], v[166:169], v[114:129]
	ds_read_b128 v[14:17], v0 offset:352
	ds_read_b128 v[138:141], v0 offset:320
	ds_read_b128 v[142:145], v0 offset:256
	ds_read_b128 v[228:231], v0 offset:288
	s_waitcnt lgkmcnt(8)
	v_mfma_f32_32x32x16_bf16 v[114:129], v[220:223], v[162:165], v[114:129]
	s_waitcnt lgkmcnt(7)
	v_mfma_f32_32x32x16_bf16 v[114:129], v[224:227], v[158:161], v[114:129]
	s_waitcnt lgkmcnt(6)
	v_mfma_f32_32x32x16_bf16 v[114:129], v[232:235], v[154:157], v[114:129]
	s_waitcnt lgkmcnt(5)
	v_mfma_f32_32x32x16_bf16 v[114:129], v[236:239], v[134:137], v[114:129]
	ds_read_b128 v[220:223], v0 offset:384
	ds_read_b128 v[224:227], v0 offset:416
	ds_read_b128 v[232:235], v0 offset:448
	ds_read_b128 v[236:239], v0 offset:480
	s_waitcnt lgkmcnt(8)
	v_mfma_f32_32x32x16_bf16 v[114:129], v[240:243], v[130:133], v[114:129]
	s_waitcnt lgkmcnt(5)
	v_mfma_f32_32x32x16_bf16 v[114:129], v[142:145], v[202:205], v[114:129]
	s_waitcnt lgkmcnt(4)
	v_mfma_f32_32x32x16_bf16 v[114:129], v[228:231], v[198:201], v[114:129]
	v_mfma_f32_32x32x16_bf16 v[114:129], v[138:141], v[194:197], v[114:129]
	v_mfma_f32_32x32x16_bf16 v[114:129], v[14:17], v[190:193], v[114:129]
	s_waitcnt vmcnt(3)
	ds_write_b128 v214, v[6:9] offset:16896
	s_waitcnt vmcnt(2)
	ds_write_b128 v214, v[10:13] offset:16912
	v_add_co_u32_e32 v8, vcc, s45, v212
	s_waitcnt lgkmcnt(0)
	s_nop 0
	v_addc_co_u32_e32 v9, vcc, 0, v213, vcc
	s_barrier
	v_lshl_add_u64 v[6:7], v[212:213], 0, s[22:23]
	global_load_dwordx4 v[142:145], v[8:9], off
	global_load_dwordx4 v[138:141], v[6:7], off offset:16
	v_mfma_f32_32x32x16_bf16 v[114:129], v[220:223], v[186:189], v[114:129]
	v_mfma_f32_32x32x16_bf16 v[114:129], v[224:227], v[182:185], v[114:129]
	v_mfma_f32_32x32x16_bf16 v[114:129], v[232:235], v[178:181], v[114:129]
	ds_read_b128 v[6:9], v0 offset:16896
	ds_read_b128 v[220:223], v0 offset:16928
	ds_read_b128 v[224:227], v0 offset:16960
	ds_read_b128 v[228:231], v0 offset:16992
	ds_read_b128 v[232:235], v0 offset:17024
	ds_read_b128 v[240:243], v0 offset:17056
	ds_read_b128 v[250:253], v0 offset:17088
	ds_read_b128 v[208:211], v0 offset:17120
	v_mfma_f32_32x32x16_bf16 v[114:129], v[236:239], v[174:177], v[114:129]
	s_waitcnt lgkmcnt(7)
	v_mfma_f32_32x32x16_bf16 v[2:17], v[6:9], v[2:5], 0
	s_waitcnt lgkmcnt(6)
	v_mfma_f32_32x32x16_bf16 v[2:17], v[220:223], v[170:173], v[2:17]
	s_waitcnt lgkmcnt(5)
	v_mfma_f32_32x32x16_bf16 v[2:17], v[224:227], v[166:169], v[2:17]
	ds_read_b128 v[166:169], v0 offset:17248
	ds_read_b128 v[170:173], v0 offset:17216
	ds_read_b128 v[220:223], v0 offset:17152
	ds_read_b128 v[224:227], v0 offset:17184
	s_waitcnt lgkmcnt(8)
	v_mfma_f32_32x32x16_bf16 v[2:17], v[228:231], v[162:165], v[2:17]
	s_waitcnt lgkmcnt(7)
	v_mfma_f32_32x32x16_bf16 v[2:17], v[232:235], v[158:161], v[2:17]
	s_waitcnt lgkmcnt(6)
	v_mfma_f32_32x32x16_bf16 v[2:17], v[240:243], v[154:157], v[2:17]
	s_waitcnt lgkmcnt(5)
	v_mfma_f32_32x32x16_bf16 v[2:17], v[250:253], v[134:137], v[2:17]
	ds_read_b128 v[134:137], v0 offset:17280
	ds_read_b128 v[154:157], v0 offset:17312
	ds_read_b128 v[158:161], v0 offset:17344
	ds_read_b128 v[162:165], v0 offset:17376
	s_waitcnt lgkmcnt(8)
	v_mfma_f32_32x32x16_bf16 v[2:17], v[208:211], v[130:133], v[2:17]
	s_waitcnt lgkmcnt(5)
	v_mfma_f32_32x32x16_bf16 v[2:17], v[220:223], v[202:205], v[2:17]
	s_waitcnt lgkmcnt(4)
	v_mfma_f32_32x32x16_bf16 v[2:17], v[224:227], v[198:201], v[2:17]
	v_mfma_f32_32x32x16_bf16 v[2:17], v[170:173], v[194:197], v[2:17]
	v_mfma_f32_32x32x16_bf16 v[2:17], v[166:169], v[190:193], v[2:17]
	v_max_f32_e32 v0, v19, v19
	v_max_f32_e32 v130, v18, v18
	v_max_f32_e32 v0, v130, v0
	v_max3_f32 v0, v0, v20, v21
	v_max3_f32 v0, v0, v22, v23
	v_max3_f32 v0, v0, v24, v25
	v_max3_f32 v0, v0, v26, v27
	v_max3_f32 v0, v0, v28, v29
	v_max3_f32 v0, v0, v30, v31
	v_max3_f32 v0, v0, v32, v33
	v_max3_f32 v0, v0, v34, v35
	v_max3_f32 v0, v0, v36, v37
	v_max3_f32 v0, v0, v38, v39
	v_max3_f32 v0, v0, v40, v41
	v_max3_f32 v0, v0, v42, v43
	v_max3_f32 v0, v0, v44, v45
	v_max3_f32 v0, v0, v46, v47
	v_max3_f32 v0, v0, v48, v49
	v_max3_f32 v0, v0, v50, v51
	v_max3_f32 v0, v0, v52, v53
	v_max3_f32 v0, v0, v54, v55
	v_max3_f32 v0, v0, v56, v57
	v_max3_f32 v0, v0, v58, v59
	v_max3_f32 v0, v0, v60, v61
	v_max3_f32 v0, v0, v62, v63
	v_max3_f32 v0, v0, v64, v65
	s_waitcnt lgkmcnt(3)
	v_mfma_f32_32x32x16_bf16 v[2:17], v[134:137], v[186:189], v[2:17]
	v_max3_f32 v0, v0, v66, v67
	v_max3_f32 v0, v0, v68, v69
	v_max3_f32 v0, v0, v70, v71
	v_max3_f32 v0, v0, v72, v73
	v_max3_f32 v0, v0, v74, v75
	v_max3_f32 v0, v0, v76, v77
	v_max3_f32 v0, v0, v78, v79
	v_max3_f32 v0, v0, v80, v81
	s_waitcnt lgkmcnt(2)
	v_mfma_f32_32x32x16_bf16 v[2:17], v[154:157], v[182:185], v[2:17]
	v_max3_f32 v0, v0, v82, v83
	v_max3_f32 v0, v0, v84, v85
	v_max3_f32 v0, v0, v86, v87
	v_max3_f32 v0, v0, v88, v89
	v_max3_f32 v0, v0, v90, v91
	v_max3_f32 v0, v0, v92, v93
	v_max3_f32 v0, v0, v94, v95
	v_max3_f32 v0, v0, v96, v97
	s_waitcnt lgkmcnt(1)
	v_mfma_f32_32x32x16_bf16 v[2:17], v[158:161], v[178:181], v[2:17]
	v_max3_f32 v0, v0, v98, v99
	v_max3_f32 v0, v0, v100, v101
	v_max3_f32 v0, v0, v102, v103
	v_max3_f32 v0, v0, v104, v105
	v_max3_f32 v0, v0, v106, v107
	v_max3_f32 v0, v0, v108, v109
	v_max3_f32 v0, v0, v110, v111
	v_max3_f32 v0, v0, v112, v113
	s_waitcnt lgkmcnt(0)
	v_mfma_f32_32x32x16_bf16 v[2:17], v[162:165], v[174:177], v[2:17]
	v_max3_f32 v0, v0, v114, v115
	v_max3_f32 v0, v0, v116, v117
	v_max3_f32 v0, v0, v118, v119
	v_max3_f32 v0, v0, v120, v121
	v_max3_f32 v0, v0, v122, v123
	v_max3_f32 v0, v0, v124, v125
	v_max3_f32 v0, v0, v126, v127
	v_max3_f32 v0, v0, v128, v129
	s_nop 3
	v_max3_f32 v0, v0, v2, v3
	v_max3_f32 v0, v0, v4, v5
	v_max3_f32 v0, v0, v6, v7
	v_max3_f32 v0, v0, v8, v9
	v_max3_f32 v0, v0, v10, v11
	v_max3_f32 v0, v0, v12, v13
	v_max3_f32 v0, v0, v14, v15
	v_and_b32_e32 v131, 64, v246
	v_max3_f32 v130, v0, v16, v17
	v_xor_b32_e32 v0, 32, v246
	v_add_u32_e32 v131, 64, v131
	v_cmp_lt_i32_e32 vcc, v0, v131
	s_waitcnt vmcnt(2)
	ds_write_b128 v214, v[150:153]
	ds_write_b128 v214, v[146:149] offset:16
	v_cndmask_b32_e32 v0, v246, v0, vcc
	v_lshlrev_b32_e32 v0, 2, v0
	ds_bpermute_b32 v131, v0, v130
	s_waitcnt lgkmcnt(0)
	s_barrier
; __device__ __forceinline__ unsigned cvtpk(float lo, float hi) { f32x2_t v = {lo, hi}; bf16x2_t b = __builtin_convertvector(v, bf16x2_t); return __builtin_bit_cast(unsigned, b); }
; __device__ __forceinline__ void unit(XLAS unsigned char* lds, const bf16_t* Qg, const bf16_t* Kg, const bf16_t* Vg, bf16_t* Og) {
;     ...
;     float l = 0.f;
;     u32x4 pw[8][2];
; #pragma unroll
;     for (int c = 0; c < 8; ++c) {
;         f32x16 p;
; #pragma unroll
;         for (int r = 0; r < 16; ++r) { p[r] = __builtin_amdgcn_exp2f(S[c][r] - mx); l += p[r]; }
; #pragma unroll
;         for (int s = 0; s < 2; ++s) { pw[c][s].x = cvtpk(p[8 * s + 0], p[8 * s + 1]); pw[c][s].y = cvtpk(p[8 * s + 2], p[8 * s + 3]); pw[c][s].z = cvtpk(p[8 * s + 4], p[8 * s + 5]); pw[c][s].w = cvtpk(p[8 * s + 6], p[8 * s + 7]); }
;     }
	s_add_u32 s48, s48, s0
	v_max_f32_e32 v131, v131, v131
	v_max_f32_e32 v154, v130, v131
	v_sub_f32_e32 v18, v18, v154
	v_sub_f32_e32 v19, v19, v154
	v_exp_f32_e32 v18, v18
	v_exp_f32_e32 v19, v19
	v_sub_f32_e32 v20, v20, v154
	v_exp_f32_e32 v20, v20
	v_sub_f32_e32 v21, v21, v154
	v_exp_f32_e32 v21, v21
	v_sub_f32_e32 v22, v22, v154
	v_exp_f32_e32 v22, v22
	v_sub_f32_e32 v23, v23, v154
	v_cvt_pk_bf16_f32 v130, v18, v19
	v_add_f32_e32 v18, 0, v18
	v_exp_f32_e32 v23, v23
	v_sub_f32_e32 v24, v24, v154
	v_add_f32_e32 v18, v19, v18
	v_exp_f32_e32 v24, v24
	v_sub_f32_e32 v25, v25, v154
	v_add_f32_e32 v18, v20, v18
	v_exp_f32_e32 v25, v25
	v_sub_f32_e32 v26, v26, v154
	v_add_f32_e32 v18, v21, v18
	v_exp_f32_e32 v26, v26
	v_sub_f32_e32 v27, v27, v154
	v_add_f32_e32 v18, v22, v18
	v_exp_f32_e32 v27, v27
	v_sub_f32_e32 v28, v28, v154
	v_add_f32_e32 v18, v23, v18
	v_exp_f32_e32 v28, v28
	v_sub_f32_e32 v29, v29, v154
	v_add_f32_e32 v18, v24, v18
	v_exp_f32_e32 v29, v29
	v_sub_f32_e32 v30, v30, v154
	v_add_f32_e32 v18, v25, v18
	v_exp_f32_e32 v30, v30
	v_sub_f32_e32 v31, v31, v154
	v_add_f32_e32 v18, v26, v18
	v_exp_f32_e32 v31, v31
	v_sub_f32_e32 v32, v32, v154
	v_add_f32_e32 v18, v27, v18
	v_exp_f32_e32 v32, v32
	v_sub_f32_e32 v33, v33, v154
	v_add_f32_e32 v18, v28, v18
	v_exp_f32_e32 v33, v33
	v_add_f32_e32 v18, v29, v18
	v_sub_f32_e32 v19, v34, v154
	v_cvt_pk_bf16_f32 v131, v20, v21
	v_add_f32_e32 v18, v30, v18
	v_exp_f32_e32 v19, v19
	v_sub_f32_e32 v20, v35, v154
	v_add_f32_e32 v18, v31, v18
	v_exp_f32_e32 v20, v20
	v_sub_f32_e32 v21, v36, v154
	v_cvt_pk_bf16_f32 v132, v22, v23
	v_add_f32_e32 v18, v32, v18
	v_exp_f32_e32 v21, v21
	v_sub_f32_e32 v22, v37, v154
	v_add_f32_e32 v18, v33, v18
	v_exp_f32_e32 v22, v22
	v_sub_f32_e32 v23, v38, v154
	v_cvt_pk_bf16_f32 v133, v24, v25
	v_exp_f32_e32 v23, v23
	v_sub_f32_e32 v24, v39, v154
	v_add_f32_e32 v18, v19, v18
	v_exp_f32_e32 v24, v24
	v_sub_f32_e32 v25, v40, v154
	v_add_f32_e32 v18, v20, v18
	v_cvt_pk_bf16_f32 v134, v26, v27
	v_exp_f32_e32 v25, v25
	v_sub_f32_e32 v26, v41, v154
	v_add_f32_e32 v18, v21, v18
	v_exp_f32_e32 v26, v26
	v_sub_f32_e32 v27, v42, v154
	v_add_f32_e32 v18, v22, v18
	v_cvt_pk_bf16_f32 v135, v28, v29
	v_exp_f32_e32 v27, v27
	v_sub_f32_e32 v28, v43, v154
	v_add_f32_e32 v18, v23, v18
	v_exp_f32_e32 v28, v28
	v_sub_f32_e32 v29, v44, v154
	v_add_f32_e32 v18, v24, v18
	v_cvt_pk_bf16_f32 v136, v30, v31
	v_exp_f32_e32 v29, v29
	v_sub_f32_e32 v30, v45, v154
	v_add_f32_e32 v18, v25, v18
	v_exp_f32_e32 v30, v30
	v_sub_f32_e32 v31, v46, v154
	v_add_f32_e32 v18, v26, v18
	v_cvt_pk_bf16_f32 v137, v32, v33
	v_exp_f32_e32 v31, v31
	v_sub_f32_e32 v32, v47, v154
	v_add_f32_e32 v18, v27, v18
	v_exp_f32_e32 v32, v32
	v_sub_f32_e32 v33, v48, v154
	v_add_f32_e32 v18, v28, v18
	v_exp_f32_e32 v33, v33
	v_sub_f32_e32 v34, v49, v154
	v_add_f32_e32 v18, v29, v18
	v_exp_f32_e32 v42, v34
	v_cvt_pk_bf16_f32 v34, v19, v20
	v_add_f32_e32 v18, v30, v18
	v_sub_f32_e32 v19, v50, v154
	v_add_f32_e32 v18, v31, v18
	v_exp_f32_e32 v19, v19
	v_sub_f32_e32 v20, v51, v154
	v_cvt_pk_bf16_f32 v35, v21, v22
	v_add_f32_e32 v18, v32, v18
	v_exp_f32_e32 v20, v20
	v_sub_f32_e32 v21, v52, v154
	v_add_f32_e32 v18, v33, v18
	v_exp_f32_e32 v21, v21
	v_sub_f32_e32 v22, v53, v154
	v_cvt_pk_bf16_f32 v36, v23, v24
	v_add_f32_e32 v18, v42, v18
	v_exp_f32_e32 v22, v22
	v_sub_f32_e32 v23, v54, v154
	v_exp_f32_e32 v23, v23
	v_sub_f32_e32 v24, v55, v154
	v_add_f32_e32 v18, v19, v18
	v_cvt_pk_bf16_f32 v37, v25, v26
	v_exp_f32_e32 v24, v24
	v_sub_f32_e32 v25, v56, v154
	v_add_f32_e32 v18, v20, v18
	v_exp_f32_e32 v25, v25
	v_sub_f32_e32 v26, v57, v154
	v_add_f32_e32 v18, v21, v18
	v_cvt_pk_bf16_f32 v38, v27, v28
	v_exp_f32_e32 v26, v26
	v_sub_f32_e32 v27, v58, v154
	v_add_f32_e32 v18, v22, v18
	v_exp_f32_e32 v27, v27
	v_sub_f32_e32 v28, v59, v154
	v_add_f32_e32 v18, v23, v18
	v_cvt_pk_bf16_f32 v39, v29, v30
	v_exp_f32_e32 v28, v28
	v_sub_f32_e32 v29, v60, v154
	v_add_f32_e32 v18, v24, v18
	v_exp_f32_e32 v29, v29
	v_sub_f32_e32 v30, v61, v154
	v_add_f32_e32 v18, v25, v18
	v_cvt_pk_bf16_f32 v40, v31, v32
	v_exp_f32_e32 v30, v30
	v_sub_f32_e32 v31, v62, v154
	v_add_f32_e32 v18, v26, v18
	v_exp_f32_e32 v31, v31
	v_sub_f32_e32 v32, v63, v154
	v_add_f32_e32 v18, v27, v18
	v_cvt_pk_bf16_f32 v41, v33, v42
	v_exp_f32_e32 v32, v32
	v_sub_f32_e32 v33, v64, v154
	v_add_f32_e32 v18, v28, v18
	v_exp_f32_e32 v33, v33
	v_sub_f32_e32 v42, v65, v154
	v_add_f32_e32 v18, v29, v18
	v_exp_f32_e32 v50, v42
	v_cvt_pk_bf16_f32 v42, v19, v20
	v_add_f32_e32 v18, v30, v18
	v_sub_f32_e32 v19, v66, v154
	v_add_f32_e32 v18, v31, v18
	v_exp_f32_e32 v19, v19
	v_sub_f32_e32 v20, v67, v154
	v_cvt_pk_bf16_f32 v43, v21, v22
	v_add_f32_e32 v18, v32, v18
	v_exp_f32_e32 v20, v20
	v_sub_f32_e32 v21, v68, v154
	v_add_f32_e32 v18, v33, v18
	v_exp_f32_e32 v21, v21
	v_sub_f32_e32 v22, v69, v154
	v_cvt_pk_bf16_f32 v44, v23, v24
	v_add_f32_e32 v18, v50, v18
	v_exp_f32_e32 v22, v22
	v_sub_f32_e32 v23, v70, v154
	v_exp_f32_e32 v23, v23
	v_sub_f32_e32 v24, v71, v154
	v_add_f32_e32 v18, v19, v18
	v_cvt_pk_bf16_f32 v45, v25, v26
	v_exp_f32_e32 v24, v24
	v_sub_f32_e32 v25, v72, v154
	v_add_f32_e32 v18, v20, v18
	v_exp_f32_e32 v25, v25
	v_sub_f32_e32 v26, v73, v154
	v_add_f32_e32 v18, v21, v18
	v_cvt_pk_bf16_f32 v46, v27, v28
	v_exp_f32_e32 v26, v26
	v_sub_f32_e32 v27, v74, v154
	v_add_f32_e32 v18, v22, v18
	v_exp_f32_e32 v27, v27
	v_sub_f32_e32 v28, v75, v154
	v_add_f32_e32 v18, v23, v18
	v_cvt_pk_bf16_f32 v47, v29, v30
	v_exp_f32_e32 v28, v28
	v_sub_f32_e32 v29, v76, v154
	v_add_f32_e32 v18, v24, v18
	v_exp_f32_e32 v29, v29
	v_sub_f32_e32 v30, v77, v154
	v_add_f32_e32 v18, v25, v18
; #define XLAS __attribute__((address_space(3)))
; __device__ __forceinline__ unsigned cvtpk(float lo, float hi) { f32x2_t v = {lo, hi}; bf16x2_t b = __builtin_convertvector(v, bf16x2_t); return __builtin_bit_cast(unsigned, b); }
; __device__ __forceinline__ void unit(XLAS unsigned char* lds, const bf16_t* Qg, const bf16_t* Kg, const bf16_t* Vg, bf16_t* Og) {
;     ...
; #pragma unroll
;     for (int c = 0; c < 8; ++c) {
;         f32x16 p;
; #pragma unroll
;         for (int r = 0; r < 16; ++r) { p[r] = __builtin_amdgcn_exp2f(S[c][r] - mx); l += p[r]; }
; #pragma unroll
;         for (int s = 0; s < 2; ++s) { pw[c][s].x = cvtpk(p[8 * s + 0], p[8 * s + 1]); pw[c][s].y = cvtpk(p[8 * s + 2], p[8 * s + 3]); pw[c][s].z = cvtpk(p[8 * s + 4], p[8 * s + 5]); pw[c][s].w = cvtpk(p[8 * s + 6], p[8 * s + 7]); }
;     }
;     l += __shfl_xor(l, 32);
;     const float rl = 1.0f / l;
;     bf16_t* obase = Og + (size_t)(wid * 32 + (lane >> 3)) * 1024 + (lane & 7) * 8;
; #pragma unroll
;     for (int db = 0; db < 8; ++db) {
;         XLAS unsigned char* buf = lds + (db & 1) * CHB;
;         *(XLAS u32x4*)(buf + wofs) = g[db & 1][0]; *(XLAS u32x4*)(buf + wofs + 16) = g[db & 1][1];
;         __syncthreads();
;         if (db < 6) { g[db & 1][0] = *(const u32x4*)(XAT_SRC(db + 10)); g[db & 1][1] = *(const u32x4*)(XAT_SRC(db + 10) + 8); }
;         f32x16 o = {};
; #pragma unroll
;         for (int kb = 0; kb < 8; ++kb)
; #pragma unroll
;             for (int s = 0; s < 2; ++s) { const bf16x8 vf = *(const XLAS bf16x8*)(buf + vro + kb * 64 + s * 32); o = __builtin_amdgcn_mfma_f32_32x32x16_bf16(vf, __builtin_bit_cast(bf16x8, pw[kb][s]), o, 0, 0, 0); }
	v_cvt_pk_bf16_f32 v48, v31, v32
	v_exp_f32_e32 v30, v30
	v_sub_f32_e32 v31, v78, v154
	v_add_f32_e32 v18, v26, v18
	v_exp_f32_e32 v31, v31
	v_sub_f32_e32 v32, v79, v154
	v_add_f32_e32 v18, v27, v18
	v_cvt_pk_bf16_f32 v49, v33, v50
	v_exp_f32_e32 v32, v32
	v_sub_f32_e32 v33, v80, v154
	v_add_f32_e32 v18, v28, v18
	v_exp_f32_e32 v33, v33
	v_sub_f32_e32 v50, v81, v154
	v_add_f32_e32 v18, v29, v18
	v_exp_f32_e32 v58, v50
	v_cvt_pk_bf16_f32 v50, v19, v20
	v_add_f32_e32 v18, v30, v18
	v_sub_f32_e32 v19, v82, v154
	v_add_f32_e32 v18, v31, v18
	v_exp_f32_e32 v19, v19
	v_sub_f32_e32 v20, v83, v154
	v_cvt_pk_bf16_f32 v51, v21, v22
	v_add_f32_e32 v18, v32, v18
	v_exp_f32_e32 v20, v20
	v_sub_f32_e32 v21, v84, v154
	v_add_f32_e32 v18, v33, v18
	v_exp_f32_e32 v21, v21
	v_sub_f32_e32 v22, v85, v154
	v_cvt_pk_bf16_f32 v52, v23, v24
	v_add_f32_e32 v18, v58, v18
	v_exp_f32_e32 v22, v22
	v_sub_f32_e32 v23, v86, v154
	v_exp_f32_e32 v23, v23
	v_sub_f32_e32 v24, v87, v154
	v_add_f32_e32 v18, v19, v18
	v_cvt_pk_bf16_f32 v53, v25, v26
	v_exp_f32_e32 v24, v24
	v_sub_f32_e32 v25, v88, v154
	v_add_f32_e32 v18, v20, v18
	v_exp_f32_e32 v25, v25
	v_sub_f32_e32 v26, v89, v154
	v_add_f32_e32 v18, v21, v18
	v_cvt_pk_bf16_f32 v54, v27, v28
	v_exp_f32_e32 v26, v26
	v_sub_f32_e32 v27, v90, v154
	v_add_f32_e32 v18, v22, v18
	v_exp_f32_e32 v27, v27
	v_sub_f32_e32 v28, v91, v154
	v_add_f32_e32 v18, v23, v18
	v_cvt_pk_bf16_f32 v55, v29, v30
	v_exp_f32_e32 v28, v28
	v_sub_f32_e32 v29, v92, v154
	v_add_f32_e32 v18, v24, v18
	v_exp_f32_e32 v29, v29
	v_sub_f32_e32 v30, v93, v154
	v_add_f32_e32 v18, v25, v18
	v_cvt_pk_bf16_f32 v56, v31, v32
	v_exp_f32_e32 v30, v30
	v_sub_f32_e32 v31, v94, v154
	v_add_f32_e32 v18, v26, v18
	v_exp_f32_e32 v31, v31
	v_sub_f32_e32 v32, v95, v154
	v_add_f32_e32 v18, v27, v18
	v_cvt_pk_bf16_f32 v57, v33, v58
	v_exp_f32_e32 v32, v32
	v_sub_f32_e32 v33, v96, v154
	v_add_f32_e32 v18, v28, v18
	v_exp_f32_e32 v33, v33
	v_sub_f32_e32 v58, v97, v154
	v_add_f32_e32 v18, v29, v18
	v_exp_f32_e32 v66, v58
	v_cvt_pk_bf16_f32 v58, v19, v20
	v_add_f32_e32 v18, v30, v18
	v_sub_f32_e32 v19, v98, v154
	v_add_f32_e32 v18, v31, v18
	v_exp_f32_e32 v19, v19
	v_sub_f32_e32 v20, v99, v154
	v_cvt_pk_bf16_f32 v59, v21, v22
	v_add_f32_e32 v18, v32, v18
	v_exp_f32_e32 v20, v20
	v_sub_f32_e32 v21, v100, v154
	v_add_f32_e32 v18, v33, v18
	v_exp_f32_e32 v21, v21
	v_sub_f32_e32 v22, v101, v154
	v_cvt_pk_bf16_f32 v60, v23, v24
	v_add_f32_e32 v18, v66, v18
	v_exp_f32_e32 v22, v22
	v_sub_f32_e32 v23, v102, v154
	v_exp_f32_e32 v23, v23
	v_sub_f32_e32 v24, v103, v154
	v_add_f32_e32 v18, v19, v18
	v_cvt_pk_bf16_f32 v61, v25, v26
	v_exp_f32_e32 v24, v24
	v_sub_f32_e32 v25, v104, v154
	v_add_f32_e32 v18, v20, v18
	v_exp_f32_e32 v25, v25
	v_sub_f32_e32 v26, v105, v154
	v_add_f32_e32 v18, v21, v18
	v_cvt_pk_bf16_f32 v62, v27, v28
	v_exp_f32_e32 v26, v26
	v_sub_f32_e32 v27, v106, v154
	v_add_f32_e32 v18, v22, v18
	v_exp_f32_e32 v27, v27
	v_sub_f32_e32 v28, v107, v154
	v_add_f32_e32 v18, v23, v18
	v_cvt_pk_bf16_f32 v63, v29, v30
	v_exp_f32_e32 v28, v28
	v_sub_f32_e32 v29, v108, v154
	v_add_f32_e32 v18, v24, v18
	v_exp_f32_e32 v29, v29
	v_sub_f32_e32 v30, v109, v154
	v_add_f32_e32 v18, v25, v18
	v_cvt_pk_bf16_f32 v64, v31, v32
	v_exp_f32_e32 v30, v30
	v_sub_f32_e32 v31, v110, v154
	v_add_f32_e32 v18, v26, v18
	v_exp_f32_e32 v31, v31
	v_sub_f32_e32 v32, v111, v154
	v_add_f32_e32 v18, v27, v18
	v_cvt_pk_bf16_f32 v65, v33, v66
	v_exp_f32_e32 v32, v32
	v_sub_f32_e32 v33, v112, v154
	v_add_f32_e32 v18, v28, v18
	v_exp_f32_e32 v33, v33
	v_sub_f32_e32 v66, v113, v154
	v_add_f32_e32 v18, v29, v18
	v_exp_f32_e32 v74, v66
	v_add_f32_e32 v18, v30, v18
	v_add_f32_e32 v18, v31, v18
	v_add_f32_e32 v18, v32, v18
	v_add_f32_e32 v18, v33, v18
	v_cvt_pk_bf16_f32 v67, v21, v22
	v_add_f32_e32 v22, v74, v18
	v_sub_f32_e32 v18, v114, v154
	v_cvt_pk_bf16_f32 v68, v23, v24
	v_exp_f32_e32 v23, v18
	v_sub_f32_e32 v18, v115, v154
	v_exp_f32_e32 v24, v18
	v_sub_f32_e32 v18, v116, v154
	v_cvt_pk_bf16_f32 v69, v25, v26
	v_exp_f32_e32 v25, v18
	v_sub_f32_e32 v18, v117, v154
	v_exp_f32_e32 v26, v18
	v_sub_f32_e32 v18, v118, v154
	v_cvt_pk_bf16_f32 v70, v27, v28
	v_exp_f32_e32 v27, v18
	v_sub_f32_e32 v18, v119, v154
	v_exp_f32_e32 v28, v18
	v_sub_f32_e32 v18, v120, v154
	v_cvt_pk_bf16_f32 v71, v29, v30
	v_exp_f32_e32 v29, v18
	v_sub_f32_e32 v18, v121, v154
	v_exp_f32_e32 v85, v18
	v_sub_f32_e32 v18, v122, v154
	v_exp_f32_e32 v90, v18
	v_sub_f32_e32 v18, v123, v154
	v_exp_f32_e32 v91, v18
	v_sub_f32_e32 v18, v124, v154
	v_exp_f32_e32 v92, v18
	v_sub_f32_e32 v18, v125, v154
	v_exp_f32_e32 v93, v18
	v_sub_f32_e32 v18, v126, v154
	v_exp_f32_e32 v94, v18
	v_sub_f32_e32 v18, v127, v154
	v_exp_f32_e32 v82, v18
	v_sub_f32_e32 v18, v128, v154
	v_exp_f32_e32 v83, v18
	v_sub_f32_e32 v18, v129, v154
	v_exp_f32_e32 v84, v18
	v_mul_u32_u24_e32 v18, 0x210, v216
	v_add3_u32 v99, 0, v18, v218
	v_cvt_pk_bf16_f32 v66, v19, v20
	ds_read_b128 v[18:21], v99
	ds_read_b128 v[86:89], v99 offset:32
	v_add_f32_e32 v22, v23, v22
	v_add_f32_e32 v22, v24, v22
	v_add_f32_e32 v22, v25, v22
	v_add_f32_e32 v22, v26, v22
	v_add_f32_e32 v22, v27, v22
	v_add_f32_e32 v22, v28, v22
	v_cvt_pk_bf16_f32 v72, v31, v32
	v_cvt_pk_bf16_f32 v73, v33, v74
	v_cvt_pk_bf16_f32 v74, v23, v24
	v_cvt_pk_bf16_f32 v75, v25, v26
	v_cvt_pk_bf16_f32 v76, v27, v28
	v_cvt_pk_bf16_f32 v77, v29, v85
	v_add_f32_e32 v95, v29, v22
	s_waitcnt lgkmcnt(1)
	v_mfma_f32_32x32x16_bf16 v[18:33], v[18:21], v[130:133], 0
	v_add_f32_e32 v85, v85, v95
	v_add_f32_e32 v85, v90, v85
	v_add_f32_e32 v85, v91, v85
	v_add_f32_e32 v85, v92, v85
	v_cvt_pk_bf16_f32 v78, v90, v91
	v_cvt_pk_bf16_f32 v79, v92, v93
	v_add_f32_e32 v85, v93, v85
	ds_read_b128 v[90:93], v99 offset:64
	s_waitcnt lgkmcnt(1)
; #define XLAS __attribute__((address_space(3)))
; __device__ __forceinline__ unsigned cvtpk(float lo, float hi) { f32x2_t v = {lo, hi}; bf16x2_t b = __builtin_convertvector(v, bf16x2_t); return __builtin_bit_cast(unsigned, b); }
; __device__ __forceinline__ void unit(XLAS unsigned char* lds, const bf16_t* Qg, const bf16_t* Kg, const bf16_t* Vg, bf16_t* Og) {
;     ...
; #pragma unroll
;     for (int c = 0; c < 8; ++c) {
;         f32x16 p;
; #pragma unroll
;         for (int r = 0; r < 16; ++r) { p[r] = __builtin_amdgcn_exp2f(S[c][r] - mx); l += p[r]; }
; #pragma unroll
;         for (int s = 0; s < 2; ++s) { pw[c][s].x = cvtpk(p[8 * s + 0], p[8 * s + 1]); pw[c][s].y = cvtpk(p[8 * s + 2], p[8 * s + 3]); pw[c][s].z = cvtpk(p[8 * s + 4], p[8 * s + 5]); pw[c][s].w = cvtpk(p[8 * s + 6], p[8 * s + 7]); }
;     }
;     l += __shfl_xor(l, 32);
;     const float rl = 1.0f / l;
;     bf16_t* obase = Og + (size_t)(wid * 32 + (lane >> 3)) * 1024 + (lane & 7) * 8;
; #pragma unroll
;     for (int db = 0; db < 8; ++db) {
;         XLAS unsigned char* buf = lds + (db & 1) * CHB;
;         *(XLAS u32x4*)(buf + wofs) = g[db & 1][0]; *(XLAS u32x4*)(buf + wofs + 16) = g[db & 1][1];
;         __syncthreads();
;         if (db < 6) { g[db & 1][0] = *(const u32x4*)(XAT_SRC(db + 10)); g[db & 1][1] = *(const u32x4*)(XAT_SRC(db + 10) + 8); }
;         f32x16 o = {};
; #pragma unroll
;         for (int kb = 0; kb < 8; ++kb)
; #pragma unroll
;             for (int s = 0; s < 2; ++s) { const bf16x8 vf = *(const XLAS bf16x8*)(buf + vro + kb * 64 + s * 32); o = __builtin_amdgcn_mfma_f32_32x32x16_bf16(vf, __builtin_bit_cast(bf16x8, pw[kb][s]), o, 0, 0, 0); }
; #pragma unroll
;         for (int g4 = 0; g4 < 4; ++g4) { u32x2 w; w.x = cvtpk(o[4 * g4] * rl, o[4 * g4 + 1] * rl); w.y = cvtpk(o[4 * g4 + 2] * rl, o[4 * g4 + 3] * rl);
;             *(XLAS u32x2*)(xs + r32 * 144 + ((db & 1) * 32 + 8 * g4 + 4 * hi) * 2) = w; }
	v_mfma_f32_32x32x16_bf16 v[18:33], v[86:89], v[134:137], v[18:33]
	v_add_f32_e32 v85, v94, v85
	v_cvt_pk_bf16_f32 v80, v94, v82
	v_add_f32_e32 v82, v82, v85
	v_add_f32_e32 v82, v83, v82
	v_cvt_pk_bf16_f32 v81, v83, v84
	v_add_f32_e32 v88, v84, v82
	ds_read_b128 v[82:85], v99 offset:96
	s_waitcnt lgkmcnt(1)
	v_mfma_f32_32x32x16_bf16 v[18:33], v[90:93], v[34:37], v[18:33]
	v_sub_f32_e32 v2, v2, v154
	v_exp_f32_e32 v89, v2
	v_sub_f32_e32 v2, v3, v154
	v_exp_f32_e32 v90, v2
	v_sub_f32_e32 v2, v4, v154
	v_exp_f32_e32 v91, v2
	v_sub_f32_e32 v2, v5, v154
	v_exp_f32_e32 v92, v2
	ds_read_b128 v[2:5], v99 offset:128
	s_waitcnt lgkmcnt(1)
	v_mfma_f32_32x32x16_bf16 v[18:33], v[82:85], v[38:41], v[18:33]
	v_sub_f32_e32 v6, v6, v154
	v_exp_f32_e32 v82, v6
	v_sub_f32_e32 v6, v7, v154
	v_exp_f32_e32 v83, v6
	v_sub_f32_e32 v6, v8, v154
	v_exp_f32_e32 v84, v6
	v_sub_f32_e32 v85, v9, v154
	ds_read_b128 v[6:9], v99 offset:160
	s_waitcnt lgkmcnt(1)
	v_mfma_f32_32x32x16_bf16 v[18:33], v[2:5], v[42:45], v[18:33]
	v_sub_f32_e32 v2, v10, v154
	v_exp_f32_e32 v10, v2
	v_sub_f32_e32 v2, v11, v154
	v_exp_f32_e32 v11, v2
	ds_read_b128 v[2:5], v99 offset:192
	v_exp_f32_e32 v85, v85
	v_sub_f32_e32 v12, v12, v154
	s_waitcnt lgkmcnt(1)
	v_mfma_f32_32x32x16_bf16 v[18:33], v[6:9], v[46:49], v[18:33]
	v_sub_f32_e32 v6, v13, v154
	v_exp_f32_e32 v13, v6
	v_sub_f32_e32 v6, v14, v154
	v_exp_f32_e32 v14, v6
	ds_read_b128 v[6:9], v99 offset:224
	v_exp_f32_e32 v12, v12
	v_sub_f32_e32 v15, v15, v154
	s_waitcnt lgkmcnt(1)
	v_mfma_f32_32x32x16_bf16 v[18:33], v[2:5], v[50:53], v[18:33]
	v_sub_f32_e32 v2, v16, v154
	v_exp_f32_e32 v16, v2
	v_sub_f32_e32 v2, v17, v154
	v_exp_f32_e32 v17, v2
	ds_read_b128 v[2:5], v99 offset:256
	v_exp_f32_e32 v15, v15
	v_cvt_pk_bf16_f32 v86, v89, v90
	s_waitcnt lgkmcnt(1)
	v_mfma_f32_32x32x16_bf16 v[18:33], v[6:9], v[54:57], v[18:33]
	v_add_f32_e32 v6, v89, v88
	v_add_f32_e32 v6, v90, v6
	v_add_f32_e32 v6, v91, v6
	v_add_f32_e32 v6, v92, v6
	v_add_f32_e32 v88, v82, v6
	ds_read_b128 v[6:9], v99 offset:288
	v_cvt_pk_bf16_f32 v87, v91, v92
	s_waitcnt lgkmcnt(1)
	v_mfma_f32_32x32x16_bf16 v[18:33], v[2:5], v[58:61], v[18:33]
	v_add_f32_e32 v2, v83, v88
	v_add_f32_e32 v2, v84, v2
	v_add_f32_e32 v2, v85, v2
	v_add_f32_e32 v2, v10, v2
	v_add_f32_e32 v2, v11, v2
	v_add_f32_e32 v88, v12, v2
	ds_read_b128 v[2:5], v99 offset:320
	s_waitcnt lgkmcnt(1)
	v_mfma_f32_32x32x16_bf16 v[18:33], v[6:9], v[62:65], v[18:33]
	v_add_f32_e32 v6, v13, v88
	v_add_f32_e32 v6, v14, v6
	v_add_f32_e32 v6, v15, v6
	v_add_f32_e32 v6, v16, v6
	v_add_f32_e32 v90, v17, v6
	ds_read_b128 v[6:9], v99 offset:352
	ds_bpermute_b32 v0, v0, v90
	s_waitcnt lgkmcnt(2)
	v_mfma_f32_32x32x16_bf16 v[18:33], v[2:5], v[66:69], v[18:33]
	ds_read_b128 v[2:5], v99 offset:384
	v_cvt_pk_bf16_f32 v88, v82, v83
	v_cvt_pk_bf16_f32 v82, v10, v11
	s_waitcnt lgkmcnt(1)
	v_add_f32_e32 v0, v90, v0
	v_div_scale_f32 v10, s[8:9], v0, v0, 1.0
	v_rcp_f32_e32 v11, v10
	v_mfma_f32_32x32x16_bf16 v[18:33], v[6:9], v[70:73], v[18:33]
	v_cvt_pk_bf16_f32 v83, v12, v13
	v_cvt_pk_bf16_f32 v89, v84, v85
	v_fma_f32 v6, -v10, v11, 1.0
	v_fmac_f32_e32 v11, v6, v11
	ds_read_b128 v[6:9], v99 offset:416
	v_cvt_pk_bf16_f32 v84, v14, v15
	v_cvt_pk_bf16_f32 v85, v16, v17
	s_waitcnt lgkmcnt(1)
	v_mfma_f32_32x32x16_bf16 v[18:33], v[2:5], v[74:77], v[18:33]
	v_div_scale_f32 v2, vcc, 1.0, v0, 1.0
	v_mul_f32_e32 v12, v2, v11
	v_fma_f32 v3, -v10, v12, v2
	v_fmac_f32_e32 v12, v3, v11
	v_fma_f32 v10, -v10, v12, v2
	ds_read_b128 v[2:5], v99 offset:448
	s_waitcnt lgkmcnt(1)
	v_mfma_f32_32x32x16_bf16 v[18:33], v[6:9], v[78:81], v[18:33]
	v_div_fmas_f32 v6, v10, v11, v12
	v_div_fixup_f32 v98, v6, v0, 1.0
	v_mul_u32_u24_e32 v0, 0x90, v216
	v_lshlrev_b32_e32 v6, 3, v217
	v_add3_u32 v0, s16, v0, v6
	ds_read_b128 v[6:9], v99 offset:480
	v_add_u32_e32 v100, 0x8800, v0
	s_waitcnt lgkmcnt(1)
	v_mfma_f32_32x32x16_bf16 v[18:33], v[2:5], v[86:89], v[18:33]
	v_add_co_u32_e32 v4, vcc, s46, v212
	v_lshl_add_u64 v[2:3], v[212:213], 0, s[34:35]
	s_nop 0
	v_addc_co_u32_e32 v5, vcc, 0, v213, vcc
	global_load_dwordx4 v[94:97], v[4:5], off
	global_load_dwordx4 v[90:93], v[2:3], off offset:16
	v_lshlrev_b32_e32 v0, 4, v215
	s_waitcnt lgkmcnt(0)
	v_mfma_f32_32x32x16_bf16 v[18:33], v[6:9], v[82:85], v[18:33]
	v_and_b32_e32 v0, 0x70, v0
	s_addc_u32 s49, s49, s15
	s_nop 9
	v_pk_mul_f32 v[2:3], v[18:19], v[98:99] op_sel_hi:[1,0]
	v_pk_mul_f32 v[4:5], v[20:21], v[98:99] op_sel_hi:[1,0]
	v_cvt_pk_bf16_f32 v2, v2, v3
	v_cvt_pk_bf16_f32 v3, v4, v5
	v_pk_mul_f32 v[4:5], v[22:23], v[98:99] op_sel_hi:[1,0]
	v_pk_mul_f32 v[6:7], v[24:25], v[98:99] op_sel_hi:[1,0]
	v_cvt_pk_bf16_f32 v4, v4, v5
	v_cvt_pk_bf16_f32 v5, v6, v7
	ds_write2_b64 v100, v[2:3], v[4:5] offset1:2
	v_pk_mul_f32 v[2:3], v[26:27], v[98:99] op_sel_hi:[1,0]
	v_pk_mul_f32 v[4:5], v[28:29], v[98:99] op_sel_hi:[1,0]
	v_cvt_pk_bf16_f32 v2, v2, v3
	v_cvt_pk_bf16_f32 v3, v4, v5
	v_pk_mul_f32 v[4:5], v[30:31], v[98:99] op_sel_hi:[1,0]
	v_pk_mul_f32 v[6:7], v[32:33], v[98:99] op_sel_hi:[1,0]
	v_cvt_pk_bf16_f32 v4, v4, v5
	v_cvt_pk_bf16_f32 v5, v6, v7
	ds_write2_b64 v100, v[2:3], v[4:5] offset0:4 offset1:6
	s_waitcnt vmcnt(3)
	ds_write_b128 v214, v[142:145] offset:16896
	s_waitcnt vmcnt(2)
	ds_write_b128 v214, v[138:141] offset:16912
	s_waitcnt lgkmcnt(0)
	s_barrier
; #define XLAS __attribute__((address_space(3)))
; __device__ __forceinline__ unsigned cvtpk(float lo, float hi) { f32x2_t v = {lo, hi}; bf16x2_t b = __builtin_convertvector(v, bf16x2_t); return __builtin_bit_cast(unsigned, b); }
; __device__ __forceinline__ void unit(XLAS unsigned char* lds, const bf16_t* Qg, const bf16_t* Kg, const bf16_t* Vg, bf16_t* Og) {
;     ...
;     for (int db = 0; db < 8; ++db) {
;         XLAS unsigned char* buf = lds + (db & 1) * CHB;
;         *(XLAS u32x4*)(buf + wofs) = g[db & 1][0]; *(XLAS u32x4*)(buf + wofs + 16) = g[db & 1][1];
;         __syncthreads();
;         if (db < 6) { g[db & 1][0] = *(const u32x4*)(XAT_SRC(db + 10)); g[db & 1][1] = *(const u32x4*)(XAT_SRC(db + 10) + 8); }
;         f32x16 o = {};
; #pragma unroll
;         for (int kb = 0; kb < 8; ++kb)
; #pragma unroll
;             for (int s = 0; s < 2; ++s) { const bf16x8 vf = *(const XLAS bf16x8*)(buf + vro + kb * 64 + s * 32); o = __builtin_amdgcn_mfma_f32_32x32x16_bf16(vf, __builtin_bit_cast(bf16x8, pw[kb][s]), o, 0, 0, 0); }
; #pragma unroll
;         for (int g4 = 0; g4 < 4; ++g4) { u32x2 w; w.x = cvtpk(o[4 * g4] * rl, o[4 * g4 + 1] * rl); w.y = cvtpk(o[4 * g4 + 2] * rl, o[4 * g4 + 3] * rl);
;             *(XLAS u32x2*)(xs + r32 * 144 + ((db & 1) * 32 + 8 * g4 + 4 * hi) * 2) = w; }
;         if (db & 1) {
; #pragma unroll
;             for (int i = 0; i < 4; ++i) { const u32x4 v = *(const XLAS u32x4*)(xs + (8 * i + (lane >> 3)) * 144 + (lane & 7) * 16); *(u32x4*)(obase + (size_t)(8 * i) * 1024 + (db >> 1) * 64) = v; }
;         }
	ds_read_b128 v[140:143], v99 offset:16896
	ds_read_b128 v[144:147], v99 offset:16928
	ds_read_b128 v[148:151], v99 offset:16960
	ds_read_b128 v[152:155], v99 offset:16992
	ds_read_b128 v[156:159], v99 offset:17024
	ds_read_b128 v[160:163], v99 offset:17056
	ds_read_b128 v[164:167], v99 offset:17088
	ds_read_b128 v[168:171], v99 offset:17120
	s_waitcnt lgkmcnt(7)
	v_mfma_f32_32x32x16_bf16 v[2:17], v[140:143], v[130:133], 0
	ds_read_b128 v[140:143], v99 offset:17152
	v_bfe_u32 v28, v215, 3, 3
	v_or_b32_e32 v26, s26, v28
	v_ashrrev_i32_e32 v27, 31, v26
	s_waitcnt lgkmcnt(7)
	v_mfma_f32_32x32x16_bf16 v[2:17], v[144:147], v[134:137], v[2:17]
	ds_read_b128 v[144:147], v99 offset:17184
	s_waitcnt lgkmcnt(7)
	v_mfma_f32_32x32x16_bf16 v[2:17], v[148:151], v[34:37], v[2:17]
	ds_read_b128 v[148:151], v99 offset:17216
	s_waitcnt lgkmcnt(7)
	v_mfma_f32_32x32x16_bf16 v[2:17], v[152:155], v[38:41], v[2:17]
	ds_read_b128 v[152:155], v99 offset:17248
	s_waitcnt lgkmcnt(7)
	v_mfma_f32_32x32x16_bf16 v[2:17], v[156:159], v[42:45], v[2:17]
	ds_read_b128 v[156:159], v99 offset:17280
	s_waitcnt lgkmcnt(7)
	v_mfma_f32_32x32x16_bf16 v[2:17], v[160:163], v[46:49], v[2:17]
	ds_read_b128 v[160:163], v99 offset:17312
	s_waitcnt lgkmcnt(7)
	v_mfma_f32_32x32x16_bf16 v[2:17], v[164:167], v[50:53], v[2:17]
	ds_read_b128 v[164:167], v99 offset:17344
	s_waitcnt lgkmcnt(7)
	v_mfma_f32_32x32x16_bf16 v[2:17], v[168:171], v[54:57], v[2:17]
	ds_read_b128 v[168:171], v99 offset:17376
	s_waitcnt lgkmcnt(7)
	v_mfma_f32_32x32x16_bf16 v[2:17], v[140:143], v[58:61], v[2:17]
	s_waitcnt lgkmcnt(6)
	v_mfma_f32_32x32x16_bf16 v[2:17], v[144:147], v[62:65], v[2:17]
	s_waitcnt lgkmcnt(5)
	v_mfma_f32_32x32x16_bf16 v[2:17], v[148:151], v[66:69], v[2:17]
	s_waitcnt lgkmcnt(4)
	v_mfma_f32_32x32x16_bf16 v[2:17], v[152:155], v[70:73], v[2:17]
	s_waitcnt lgkmcnt(3)
	v_mfma_f32_32x32x16_bf16 v[2:17], v[156:159], v[74:77], v[2:17]
	s_waitcnt lgkmcnt(2)
	v_mfma_f32_32x32x16_bf16 v[2:17], v[160:163], v[78:81], v[2:17]
	s_waitcnt lgkmcnt(1)
	v_mfma_f32_32x32x16_bf16 v[2:17], v[164:167], v[86:89], v[2:17]
	v_lshlrev_b64 v[18:19], 11, v[26:27]
	v_lshl_add_u64 v[18:19], s[4:5], 0, v[18:19]
	v_lshl_add_u64 v[26:27], v[18:19], 0, v[0:1]
	v_lshl_add_u64 v[18:19], v[212:213], 0, s[36:37]
	s_mov_b64 s[4:5], 0
	s_waitcnt lgkmcnt(0)
	v_mfma_f32_32x32x16_bf16 v[2:17], v[168:171], v[82:85], v[2:17]
	s_nop 11
	v_pk_mul_f32 v[2:3], v[2:3], v[98:99] op_sel_hi:[1,0]
	v_pk_mul_f32 v[4:5], v[4:5], v[98:99] op_sel_hi:[1,0]
	v_cvt_pk_bf16_f32 v2, v2, v3
	v_cvt_pk_bf16_f32 v3, v4, v5
	v_pk_mul_f32 v[4:5], v[6:7], v[98:99] op_sel_hi:[1,0]
	v_pk_mul_f32 v[6:7], v[8:9], v[98:99] op_sel_hi:[1,0]
	v_cvt_pk_bf16_f32 v4, v4, v5
	v_cvt_pk_bf16_f32 v5, v6, v7
	ds_write2_b64 v100, v[2:3], v[4:5] offset0:8 offset1:10
	v_pk_mul_f32 v[2:3], v[10:11], v[98:99] op_sel_hi:[1,0]
	v_pk_mul_f32 v[4:5], v[12:13], v[98:99] op_sel_hi:[1,0]
	v_cvt_pk_bf16_f32 v2, v2, v3
	v_cvt_pk_bf16_f32 v3, v4, v5
	v_pk_mul_f32 v[4:5], v[14:15], v[98:99] op_sel_hi:[1,0]
	v_pk_mul_f32 v[6:7], v[16:17], v[98:99] op_sel_hi:[1,0]
	v_cvt_pk_bf16_f32 v4, v4, v5
	v_cvt_pk_bf16_f32 v5, v6, v7
	ds_write2_b64 v100, v[2:3], v[4:5] offset0:12 offset1:14
	v_mul_u32_u24_e32 v2, 0x90, v28
	v_add_co_u32_e32 v6, vcc, s47, v212
	v_add3_u32 v0, s16, v0, v2
	s_nop 0
	v_addc_co_u32_e32 v7, vcc, 0, v213, vcc
	ds_read_b128 v[2:5], v0 offset:34816
	global_load_dwordx4 v[102:105], v[6:7], off
	global_load_dwordx4 v[106:109], v[18:19], off offset:16
	ds_read_b128 v[6:9], v0 offset:35968
	v_add_co_u32_e32 v28, vcc, s28, v26
	s_waitcnt lgkmcnt(1)
	global_store_dwordx4 v[26:27], v[2:5], off
	v_addc_co_u32_e32 v29, vcc, 0, v27, vcc
	ds_read_b128 v[2:5], v0 offset:37120
	s_waitcnt lgkmcnt(1)
	global_store_dwordx4 v[28:29], v[6:9], off
	ds_read_b128 v[6:9], v0 offset:38272
	v_add_co_u32_e32 v30, vcc, s29, v26
	s_nop 1
	v_addc_co_u32_e32 v31, vcc, 0, v27, vcc
	v_add_co_u32_e32 v32, vcc, s42, v26
	s_waitcnt lgkmcnt(1)
	global_store_dwordx4 v[30:31], v[2:5], off
	v_addc_co_u32_e32 v33, vcc, 0, v27, vcc
	s_waitcnt lgkmcnt(0)
	global_store_dwordx4 v[32:33], v[6:9], off
	s_waitcnt vmcnt(7)
	ds_write_b128 v214, v[94:97]
	s_waitcnt vmcnt(6)
	ds_write_b128 v214, v[90:93] offset:16
	s_waitcnt lgkmcnt(0)
	s_barrier
; #define XLAS __attribute__((address_space(3)))
; __device__ __forceinline__ unsigned cvtpk(float lo, float hi) { f32x2_t v = {lo, hi}; bf16x2_t b = __builtin_convertvector(v, bf16x2_t); return __builtin_bit_cast(unsigned, b); }
; __device__ __forceinline__ void unit(XLAS unsigned char* lds, const bf16_t* Qg, const bf16_t* Kg, const bf16_t* Vg, bf16_t* Og) {
;     ...
;     for (int db = 0; db < 8; ++db) {
;         XLAS unsigned char* buf = lds + (db & 1) * CHB;
;         *(XLAS u32x4*)(buf + wofs) = g[db & 1][0]; *(XLAS u32x4*)(buf + wofs + 16) = g[db & 1][1];
;         __syncthreads();
;         if (db < 6) { g[db & 1][0] = *(const u32x4*)(XAT_SRC(db + 10)); g[db & 1][1] = *(const u32x4*)(XAT_SRC(db + 10) + 8); }
;         f32x16 o = {};
; #pragma unroll
;         for (int kb = 0; kb < 8; ++kb)
; #pragma unroll
;             for (int s = 0; s < 2; ++s) { const bf16x8 vf = *(const XLAS bf16x8*)(buf + vro + kb * 64 + s * 32); o = __builtin_amdgcn_mfma_f32_32x32x16_bf16(vf, __builtin_bit_cast(bf16x8, pw[kb][s]), o, 0, 0, 0); }
; #pragma unroll
;         for (int g4 = 0; g4 < 4; ++g4) { u32x2 w; w.x = cvtpk(o[4 * g4] * rl, o[4 * g4 + 1] * rl); w.y = cvtpk(o[4 * g4 + 2] * rl, o[4 * g4 + 3] * rl);
;             *(XLAS u32x2*)(xs + r32 * 144 + ((db & 1) * 32 + 8 * g4 + 4 * hi) * 2) = w; }
;         if (db & 1) {
; #pragma unroll
;             for (int i = 0; i < 4; ++i) { const u32x4 v = *(const XLAS u32x4*)(xs + (8 * i + (lane >> 3)) * 144 + (lane & 7) * 16); *(u32x4*)(obase + (size_t)(8 * i) * 1024 + (db >> 1) * 64) = v; }
;         }
	ds_read_b128 v[140:143], v99
	ds_read_b128 v[144:147], v99 offset:32
	ds_read_b128 v[148:151], v99 offset:64
	ds_read_b128 v[152:155], v99 offset:96
	ds_read_b128 v[156:159], v99 offset:128
	ds_read_b128 v[160:163], v99 offset:160
	ds_read_b128 v[164:167], v99 offset:192
	ds_read_b128 v[168:171], v99 offset:224
	s_waitcnt lgkmcnt(7)
	v_mfma_f32_32x32x16_bf16 v[2:17], v[140:143], v[130:133], 0
	ds_read_b128 v[140:143], v99 offset:256
	s_waitcnt lgkmcnt(7)
	v_mfma_f32_32x32x16_bf16 v[2:17], v[144:147], v[134:137], v[2:17]
	ds_read_b128 v[144:147], v99 offset:288
	s_waitcnt lgkmcnt(7)
	v_mfma_f32_32x32x16_bf16 v[2:17], v[148:151], v[34:37], v[2:17]
	ds_read_b128 v[148:151], v99 offset:320
	s_waitcnt lgkmcnt(7)
	v_mfma_f32_32x32x16_bf16 v[2:17], v[152:155], v[38:41], v[2:17]
	ds_read_b128 v[152:155], v99 offset:352
	s_waitcnt lgkmcnt(7)
	v_mfma_f32_32x32x16_bf16 v[2:17], v[156:159], v[42:45], v[2:17]
	ds_read_b128 v[156:159], v99 offset:384
	s_waitcnt lgkmcnt(7)
	v_mfma_f32_32x32x16_bf16 v[2:17], v[160:163], v[46:49], v[2:17]
	ds_read_b128 v[160:163], v99 offset:416
	s_waitcnt lgkmcnt(7)
	v_mfma_f32_32x32x16_bf16 v[2:17], v[164:167], v[50:53], v[2:17]
	ds_read_b128 v[164:167], v99 offset:448
	s_waitcnt lgkmcnt(7)
	v_mfma_f32_32x32x16_bf16 v[2:17], v[168:171], v[54:57], v[2:17]
	ds_read_b128 v[168:171], v99 offset:480
	s_waitcnt lgkmcnt(7)
	v_mfma_f32_32x32x16_bf16 v[2:17], v[140:143], v[58:61], v[2:17]
	s_waitcnt lgkmcnt(6)
	v_mfma_f32_32x32x16_bf16 v[2:17], v[144:147], v[62:65], v[2:17]
	s_waitcnt lgkmcnt(5)
	v_mfma_f32_32x32x16_bf16 v[2:17], v[148:151], v[66:69], v[2:17]
	s_waitcnt lgkmcnt(4)
	v_mfma_f32_32x32x16_bf16 v[2:17], v[152:155], v[70:73], v[2:17]
	s_waitcnt lgkmcnt(3)
	v_mfma_f32_32x32x16_bf16 v[2:17], v[156:159], v[74:77], v[2:17]
	s_waitcnt lgkmcnt(2)
	v_mfma_f32_32x32x16_bf16 v[2:17], v[160:163], v[78:81], v[2:17]
	s_waitcnt lgkmcnt(1)
	v_mfma_f32_32x32x16_bf16 v[2:17], v[164:167], v[86:89], v[2:17]
	v_add_co_u32_e32 v20, vcc, s17, v212
	v_lshl_add_u64 v[18:19], v[212:213], 0, s[30:31]
	s_nop 0
	v_addc_co_u32_e32 v21, vcc, 0, v213, vcc
	global_load_dwordx4 v[22:25], v[20:21], off
	s_nop 0
	global_load_dwordx4 v[18:21], v[18:19], off offset:16
	s_waitcnt lgkmcnt(0)
	v_mfma_f32_32x32x16_bf16 v[2:17], v[168:171], v[82:85], v[2:17]
	s_nop 11
	v_pk_mul_f32 v[2:3], v[2:3], v[98:99] op_sel_hi:[1,0]
	v_pk_mul_f32 v[4:5], v[4:5], v[98:99] op_sel_hi:[1,0]
	v_cvt_pk_bf16_f32 v2, v2, v3
	v_cvt_pk_bf16_f32 v3, v4, v5
	v_pk_mul_f32 v[4:5], v[6:7], v[98:99] op_sel_hi:[1,0]
	v_pk_mul_f32 v[6:7], v[8:9], v[98:99] op_sel_hi:[1,0]
	v_cvt_pk_bf16_f32 v4, v4, v5
	v_cvt_pk_bf16_f32 v5, v6, v7
	ds_write2_b64 v100, v[2:3], v[4:5] offset1:2
	v_pk_mul_f32 v[2:3], v[10:11], v[98:99] op_sel_hi:[1,0]
	v_pk_mul_f32 v[4:5], v[12:13], v[98:99] op_sel_hi:[1,0]
	v_cvt_pk_bf16_f32 v2, v2, v3
	v_cvt_pk_bf16_f32 v3, v4, v5
	v_pk_mul_f32 v[4:5], v[14:15], v[98:99] op_sel_hi:[1,0]
	v_pk_mul_f32 v[6:7], v[16:17], v[98:99] op_sel_hi:[1,0]
	v_cvt_pk_bf16_f32 v4, v4, v5
	v_cvt_pk_bf16_f32 v5, v6, v7
	ds_write2_b64 v100, v[2:3], v[4:5] offset0:4 offset1:6
	s_waitcnt vmcnt(7)
	ds_write_b128 v214, v[102:105] offset:16896
	s_waitcnt vmcnt(6)
	ds_write_b128 v214, v[106:109] offset:16912
	s_waitcnt lgkmcnt(0)
	s_barrier
	ds_read_b128 v[140:143], v99 offset:16896
	ds_read_b128 v[144:147], v99 offset:16928
	ds_read_b128 v[148:151], v99 offset:16960
	ds_read_b128 v[152:155], v99 offset:16992
	ds_read_b128 v[156:159], v99 offset:17024
	ds_read_b128 v[160:163], v99 offset:17056
	ds_read_b128 v[164:167], v99 offset:17088
	ds_read_b128 v[168:171], v99 offset:17120
	s_waitcnt lgkmcnt(7)
	v_mfma_f32_32x32x16_bf16 v[2:17], v[140:143], v[130:133], 0
	ds_read_b128 v[140:143], v99 offset:17152
	v_lshl_add_u64 v[102:103], v[212:213], 0, s[38:39]
	s_waitcnt lgkmcnt(7)
	v_mfma_f32_32x32x16_bf16 v[2:17], v[144:147], v[134:137], v[2:17]
	ds_read_b128 v[144:147], v99 offset:17184
	s_waitcnt lgkmcnt(7)
	v_mfma_f32_32x32x16_bf16 v[2:17], v[148:151], v[34:37], v[2:17]
	ds_read_b128 v[148:151], v99 offset:17216
	s_waitcnt lgkmcnt(7)
	v_mfma_f32_32x32x16_bf16 v[2:17], v[152:155], v[38:41], v[2:17]
	ds_read_b128 v[152:155], v99 offset:17248
	s_waitcnt lgkmcnt(7)
	v_mfma_f32_32x32x16_bf16 v[2:17], v[156:159], v[42:45], v[2:17]
	ds_read_b128 v[156:159], v99 offset:17280
	s_waitcnt lgkmcnt(7)
	v_mfma_f32_32x32x16_bf16 v[2:17], v[160:163], v[46:49], v[2:17]
	ds_read_b128 v[160:163], v99 offset:17312
	s_waitcnt lgkmcnt(7)
	v_mfma_f32_32x32x16_bf16 v[2:17], v[164:167], v[50:53], v[2:17]
	ds_read_b128 v[164:167], v99 offset:17344
	s_waitcnt lgkmcnt(7)
	v_mfma_f32_32x32x16_bf16 v[2:17], v[168:171], v[54:57], v[2:17]
	ds_read_b128 v[168:171], v99 offset:17376
	s_waitcnt lgkmcnt(7)
	v_mfma_f32_32x32x16_bf16 v[2:17], v[140:143], v[58:61], v[2:17]
	s_waitcnt lgkmcnt(6)
	v_mfma_f32_32x32x16_bf16 v[2:17], v[144:147], v[62:65], v[2:17]
	s_waitcnt lgkmcnt(5)
	v_mfma_f32_32x32x16_bf16 v[2:17], v[148:151], v[66:69], v[2:17]
	s_waitcnt lgkmcnt(4)
	v_mfma_f32_32x32x16_bf16 v[2:17], v[152:155], v[70:73], v[2:17]
	s_waitcnt lgkmcnt(3)
	v_mfma_f32_32x32x16_bf16 v[2:17], v[156:159], v[74:77], v[2:17]
	s_waitcnt lgkmcnt(2)
	v_mfma_f32_32x32x16_bf16 v[2:17], v[160:163], v[78:81], v[2:17]
	s_waitcnt lgkmcnt(1)
	v_mfma_f32_32x32x16_bf16 v[2:17], v[164:167], v[86:89], v[2:17]
	v_add_co_u32_e32 v90, vcc, s27, v212
	s_nop 1
	v_addc_co_u32_e32 v91, vcc, 0, v213, vcc
	s_waitcnt lgkmcnt(0)
	v_mfma_f32_32x32x16_bf16 v[2:17], v[168:171], v[82:85], v[2:17]
	s_nop 11
	v_pk_mul_f32 v[2:3], v[98:99], v[2:3] op_sel_hi:[0,1]
	v_pk_mul_f32 v[4:5], v[98:99], v[4:5] op_sel_hi:[0,1]
	v_cvt_pk_bf16_f32 v2, v2, v3
	v_cvt_pk_bf16_f32 v3, v4, v5
	v_pk_mul_f32 v[4:5], v[98:99], v[6:7] op_sel_hi:[0,1]
	v_pk_mul_f32 v[6:7], v[98:99], v[8:9] op_sel_hi:[0,1]
	v_cvt_pk_bf16_f32 v4, v4, v5
	v_cvt_pk_bf16_f32 v5, v6, v7
	ds_write2_b64 v100, v[2:3], v[4:5] offset0:8 offset1:10
	v_pk_mul_f32 v[2:3], v[98:99], v[10:11] op_sel_hi:[0,1]
	v_pk_mul_f32 v[4:5], v[98:99], v[12:13] op_sel_hi:[0,1]
	v_cvt_pk_bf16_f32 v2, v2, v3
	v_cvt_pk_bf16_f32 v3, v4, v5
	v_pk_mul_f32 v[4:5], v[98:99], v[14:15] op_sel_hi:[0,1]
	v_pk_mul_f32 v[6:7], v[98:99], v[16:17] op_sel_hi:[0,1]
	v_cvt_pk_bf16_f32 v4, v4, v5
	v_cvt_pk_bf16_f32 v5, v6, v7
	ds_write2_b64 v100, v[2:3], v[4:5] offset0:12 offset1:14
	ds_read_b128 v[2:5], v0 offset:34816
	ds_read_b128 v[6:9], v0 offset:35968
	ds_read_b128 v[10:13], v0 offset:37120
	ds_read_b128 v[14:17], v0 offset:38272
	global_load_dwordx4 v[90:93], v[90:91], off
	s_nop 0
	global_load_dwordx4 v[94:97], v[102:103], off offset:16
	s_waitcnt lgkmcnt(3)
	global_store_dwordx4 v[26:27], v[2:5], off offset:128
	s_waitcnt lgkmcnt(2)
	global_store_dwordx4 v[28:29], v[6:9], off offset:128
	s_waitcnt lgkmcnt(1)
	global_store_dwordx4 v[30:31], v[10:13], off offset:128
	s_waitcnt lgkmcnt(0)
	global_store_dwordx4 v[32:33], v[14:17], off offset:128
	s_waitcnt vmcnt(7)
	ds_write_b128 v214, v[22:25]
	s_waitcnt vmcnt(6)
	ds_write_b128 v214, v[18:21] offset:16
	s_waitcnt lgkmcnt(0)
	s_barrier
; #define XLAS __attribute__((address_space(3)))
; __device__ __forceinline__ unsigned cvtpk(float lo, float hi) { f32x2_t v = {lo, hi}; bf16x2_t b = __builtin_convertvector(v, bf16x2_t); return __builtin_bit_cast(unsigned, b); }
; __device__ __forceinline__ void unit(XLAS unsigned char* lds, const bf16_t* Qg, const bf16_t* Kg, const bf16_t* Vg, bf16_t* Og) {
;     ...
;     for (int db = 0; db < 8; ++db) {
;         XLAS unsigned char* buf = lds + (db & 1) * CHB;
;         *(XLAS u32x4*)(buf + wofs) = g[db & 1][0]; *(XLAS u32x4*)(buf + wofs + 16) = g[db & 1][1];
;         __syncthreads();
;         if (db < 6) { g[db & 1][0] = *(const u32x4*)(XAT_SRC(db + 10)); g[db & 1][1] = *(const u32x4*)(XAT_SRC(db + 10) + 8); }
;         f32x16 o = {};
; #pragma unroll
;         for (int kb = 0; kb < 8; ++kb)
; #pragma unroll
;             for (int s = 0; s < 2; ++s) { const bf16x8 vf = *(const XLAS bf16x8*)(buf + vro + kb * 64 + s * 32); o = __builtin_amdgcn_mfma_f32_32x32x16_bf16(vf, __builtin_bit_cast(bf16x8, pw[kb][s]), o, 0, 0, 0); }
; #pragma unroll
;         for (int g4 = 0; g4 < 4; ++g4) { u32x2 w; w.x = cvtpk(o[4 * g4] * rl, o[4 * g4 + 1] * rl); w.y = cvtpk(o[4 * g4 + 2] * rl, o[4 * g4 + 3] * rl);
;             *(XLAS u32x2*)(xs + r32 * 144 + ((db & 1) * 32 + 8 * g4 + 4 * hi) * 2) = w; }
;         if (db & 1) {
; #pragma unroll
;             for (int i = 0; i < 4; ++i) { const u32x4 v = *(const XLAS u32x4*)(xs + (8 * i + (lane >> 3)) * 144 + (lane & 7) * 16); *(u32x4*)(obase + (size_t)(8 * i) * 1024 + (db >> 1) * 64) = v; }
;         }
	ds_read_b128 v[140:143], v99
	ds_read_b128 v[144:147], v99 offset:32
	ds_read_b128 v[148:151], v99 offset:64
	ds_read_b128 v[152:155], v99 offset:96
	ds_read_b128 v[156:159], v99 offset:128
	ds_read_b128 v[160:163], v99 offset:160
	ds_read_b128 v[164:167], v99 offset:192
	ds_read_b128 v[168:171], v99 offset:224
	s_waitcnt lgkmcnt(7)
	v_mfma_f32_32x32x16_bf16 v[2:17], v[140:143], v[130:133], 0
	ds_read_b128 v[140:143], v99 offset:256
	s_waitcnt lgkmcnt(7)
	v_mfma_f32_32x32x16_bf16 v[2:17], v[144:147], v[134:137], v[2:17]
	ds_read_b128 v[144:147], v99 offset:288
	s_waitcnt lgkmcnt(7)
	v_mfma_f32_32x32x16_bf16 v[2:17], v[148:151], v[34:37], v[2:17]
	ds_read_b128 v[148:151], v99 offset:320
	s_waitcnt lgkmcnt(7)
	v_mfma_f32_32x32x16_bf16 v[2:17], v[152:155], v[38:41], v[2:17]
	ds_read_b128 v[152:155], v99 offset:352
	s_waitcnt lgkmcnt(7)
	v_mfma_f32_32x32x16_bf16 v[2:17], v[156:159], v[42:45], v[2:17]
	ds_read_b128 v[156:159], v99 offset:384
	s_waitcnt lgkmcnt(7)
	v_mfma_f32_32x32x16_bf16 v[2:17], v[160:163], v[46:49], v[2:17]
	ds_read_b128 v[160:163], v99 offset:416
	s_waitcnt lgkmcnt(7)
	v_mfma_f32_32x32x16_bf16 v[2:17], v[164:167], v[50:53], v[2:17]
	ds_read_b128 v[164:167], v99 offset:448
	s_waitcnt lgkmcnt(7)
	v_mfma_f32_32x32x16_bf16 v[2:17], v[168:171], v[54:57], v[2:17]
	ds_read_b128 v[168:171], v99 offset:480
	s_waitcnt lgkmcnt(7)
	v_mfma_f32_32x32x16_bf16 v[2:17], v[140:143], v[58:61], v[2:17]
	s_waitcnt lgkmcnt(6)
	v_mfma_f32_32x32x16_bf16 v[2:17], v[144:147], v[62:65], v[2:17]
	s_waitcnt lgkmcnt(5)
	v_mfma_f32_32x32x16_bf16 v[2:17], v[148:151], v[66:69], v[2:17]
	s_waitcnt lgkmcnt(4)
	v_mfma_f32_32x32x16_bf16 v[2:17], v[152:155], v[70:73], v[2:17]
	s_waitcnt lgkmcnt(3)
	v_mfma_f32_32x32x16_bf16 v[2:17], v[156:159], v[74:77], v[2:17]
	s_waitcnt lgkmcnt(2)
	v_mfma_f32_32x32x16_bf16 v[2:17], v[160:163], v[78:81], v[2:17]
	s_waitcnt lgkmcnt(1)
	v_mfma_f32_32x32x16_bf16 v[2:17], v[164:167], v[86:89], v[2:17]
	v_add_co_u32_e32 v20, vcc, s58, v212
	v_lshl_add_u64 v[18:19], v[212:213], 0, s[56:57]
	s_nop 0
	v_addc_co_u32_e32 v21, vcc, 0, v213, vcc
	global_load_dwordx4 v[22:25], v[20:21], off
	s_nop 0
	global_load_dwordx4 v[18:21], v[18:19], off offset:16
	s_waitcnt lgkmcnt(0)
	v_mfma_f32_32x32x16_bf16 v[2:17], v[168:171], v[82:85], v[2:17]
	v_lshl_add_u64 v[102:103], v[212:213], 0, s[60:61]
	s_nop 10
	v_pk_mul_f32 v[2:3], v[98:99], v[2:3] op_sel_hi:[0,1]
	v_pk_mul_f32 v[4:5], v[98:99], v[4:5] op_sel_hi:[0,1]
	v_cvt_pk_bf16_f32 v2, v2, v3
	v_cvt_pk_bf16_f32 v3, v4, v5
	v_pk_mul_f32 v[4:5], v[98:99], v[6:7] op_sel_hi:[0,1]
	v_pk_mul_f32 v[6:7], v[98:99], v[8:9] op_sel_hi:[0,1]
	v_cvt_pk_bf16_f32 v4, v4, v5
	v_cvt_pk_bf16_f32 v5, v6, v7
	ds_write2_b64 v100, v[2:3], v[4:5] offset1:2
	v_pk_mul_f32 v[2:3], v[98:99], v[10:11] op_sel_hi:[0,1]
	v_pk_mul_f32 v[4:5], v[98:99], v[12:13] op_sel_hi:[0,1]
	v_cvt_pk_bf16_f32 v2, v2, v3
	v_cvt_pk_bf16_f32 v3, v4, v5
	v_pk_mul_f32 v[4:5], v[98:99], v[14:15] op_sel_hi:[0,1]
	v_pk_mul_f32 v[6:7], v[98:99], v[16:17] op_sel_hi:[0,1]
	v_cvt_pk_bf16_f32 v4, v4, v5
	v_cvt_pk_bf16_f32 v5, v6, v7
	ds_write2_b64 v100, v[2:3], v[4:5] offset0:4 offset1:6
	s_waitcnt vmcnt(7)
	ds_write_b128 v214, v[90:93] offset:16896
	s_waitcnt vmcnt(6)
	ds_write_b128 v214, v[94:97] offset:16912
	s_waitcnt lgkmcnt(0)
	s_barrier
	ds_read_b128 v[140:143], v99 offset:16896
	ds_read_b128 v[144:147], v99 offset:16928
	ds_read_b128 v[148:151], v99 offset:16960
	ds_read_b128 v[152:155], v99 offset:16992
	ds_read_b128 v[156:159], v99 offset:17024
	ds_read_b128 v[160:163], v99 offset:17056
	ds_read_b128 v[164:167], v99 offset:17088
	ds_read_b128 v[168:171], v99 offset:17120
	s_waitcnt lgkmcnt(7)
	v_mfma_f32_32x32x16_bf16 v[2:17], v[140:143], v[130:133], 0
	ds_read_b128 v[140:143], v99 offset:17152
	s_waitcnt lgkmcnt(7)
	v_mfma_f32_32x32x16_bf16 v[2:17], v[144:147], v[134:137], v[2:17]
	ds_read_b128 v[144:147], v99 offset:17184
	s_waitcnt lgkmcnt(7)
	v_mfma_f32_32x32x16_bf16 v[2:17], v[148:151], v[34:37], v[2:17]
	ds_read_b128 v[148:151], v99 offset:17216
	s_waitcnt lgkmcnt(7)
	v_mfma_f32_32x32x16_bf16 v[2:17], v[152:155], v[38:41], v[2:17]
	ds_read_b128 v[152:155], v99 offset:17248
	s_waitcnt lgkmcnt(7)
	v_mfma_f32_32x32x16_bf16 v[2:17], v[156:159], v[42:45], v[2:17]
	ds_read_b128 v[156:159], v99 offset:17280
	s_waitcnt lgkmcnt(7)
	v_mfma_f32_32x32x16_bf16 v[2:17], v[160:163], v[46:49], v[2:17]
	ds_read_b128 v[160:163], v99 offset:17312
	s_waitcnt lgkmcnt(7)
	v_mfma_f32_32x32x16_bf16 v[2:17], v[164:167], v[50:53], v[2:17]
	ds_read_b128 v[164:167], v99 offset:17344
	s_waitcnt lgkmcnt(7)
	v_mfma_f32_32x32x16_bf16 v[2:17], v[168:171], v[54:57], v[2:17]
	ds_read_b128 v[168:171], v99 offset:17376
	s_waitcnt lgkmcnt(7)
	v_mfma_f32_32x32x16_bf16 v[2:17], v[140:143], v[58:61], v[2:17]
	s_waitcnt lgkmcnt(6)
	v_mfma_f32_32x32x16_bf16 v[2:17], v[144:147], v[62:65], v[2:17]
	s_waitcnt lgkmcnt(5)
	v_mfma_f32_32x32x16_bf16 v[2:17], v[148:151], v[66:69], v[2:17]
	s_waitcnt lgkmcnt(4)
	v_mfma_f32_32x32x16_bf16 v[2:17], v[152:155], v[70:73], v[2:17]
	s_waitcnt lgkmcnt(3)
	v_mfma_f32_32x32x16_bf16 v[2:17], v[156:159], v[74:77], v[2:17]
	s_waitcnt lgkmcnt(2)
	v_mfma_f32_32x32x16_bf16 v[2:17], v[160:163], v[78:81], v[2:17]
	s_waitcnt lgkmcnt(1)
	v_mfma_f32_32x32x16_bf16 v[2:17], v[164:167], v[86:89], v[2:17]
	v_add_co_u32_e32 v90, vcc, s59, v212
	s_nop 1
	v_addc_co_u32_e32 v91, vcc, 0, v213, vcc
	s_waitcnt lgkmcnt(0)
	v_mfma_f32_32x32x16_bf16 v[2:17], v[168:171], v[82:85], v[2:17]
	s_nop 11
	v_pk_mul_f32 v[2:3], v[98:99], v[2:3] op_sel_hi:[0,1]
	v_pk_mul_f32 v[4:5], v[98:99], v[4:5] op_sel_hi:[0,1]
	v_cvt_pk_bf16_f32 v2, v2, v3
	v_cvt_pk_bf16_f32 v3, v4, v5
	v_pk_mul_f32 v[4:5], v[98:99], v[6:7] op_sel_hi:[0,1]
	v_pk_mul_f32 v[6:7], v[98:99], v[8:9] op_sel_hi:[0,1]
	v_cvt_pk_bf16_f32 v4, v4, v5
	v_cvt_pk_bf16_f32 v5, v6, v7
	ds_write2_b64 v100, v[2:3], v[4:5] offset0:8 offset1:10
	v_pk_mul_f32 v[2:3], v[98:99], v[10:11] op_sel_hi:[0,1]
	v_pk_mul_f32 v[4:5], v[98:99], v[12:13] op_sel_hi:[0,1]
	v_cvt_pk_bf16_f32 v2, v2, v3
	v_cvt_pk_bf16_f32 v3, v4, v5
	v_pk_mul_f32 v[4:5], v[98:99], v[14:15] op_sel_hi:[0,1]
	v_pk_mul_f32 v[6:7], v[98:99], v[16:17] op_sel_hi:[0,1]
	v_cvt_pk_bf16_f32 v4, v4, v5
	v_cvt_pk_bf16_f32 v5, v6, v7
	ds_write2_b64 v100, v[2:3], v[4:5] offset0:12 offset1:14
	ds_read_b128 v[2:5], v0 offset:34816
	ds_read_b128 v[6:9], v0 offset:35968
	ds_read_b128 v[10:13], v0 offset:37120
	ds_read_b128 v[14:17], v0 offset:38272
	global_load_dwordx4 v[90:93], v[90:91], off
	s_nop 0
	global_load_dwordx4 v[94:97], v[102:103], off offset:16
	s_waitcnt lgkmcnt(3)
	global_store_dwordx4 v[26:27], v[2:5], off offset:256
	s_waitcnt lgkmcnt(2)
	global_store_dwordx4 v[28:29], v[6:9], off offset:256
	s_waitcnt lgkmcnt(1)
	global_store_dwordx4 v[30:31], v[10:13], off offset:256
	s_waitcnt lgkmcnt(0)
	global_store_dwordx4 v[32:33], v[14:17], off offset:256
	s_waitcnt vmcnt(7)
	ds_write_b128 v214, v[22:25]
	s_waitcnt vmcnt(6)
	ds_write_b128 v214, v[18:21] offset:16
	s_waitcnt lgkmcnt(0)
	s_barrier
; #define XLAS __attribute__((address_space(3)))
; __device__ __forceinline__ unsigned cvtpk(float lo, float hi) { f32x2_t v = {lo, hi}; bf16x2_t b = __builtin_convertvector(v, bf16x2_t); return __builtin_bit_cast(unsigned, b); }
; __device__ __forceinline__ void unit(XLAS unsigned char* lds, const bf16_t* Qg, const bf16_t* Kg, const bf16_t* Vg, bf16_t* Og) {
;     ...
;     for (int db = 0; db < 8; ++db) {
;         XLAS unsigned char* buf = lds + (db & 1) * CHB;
;         *(XLAS u32x4*)(buf + wofs) = g[db & 1][0]; *(XLAS u32x4*)(buf + wofs + 16) = g[db & 1][1];
;         __syncthreads();
;         if (db < 6) { g[db & 1][0] = *(const u32x4*)(XAT_SRC(db + 10)); g[db & 1][1] = *(const u32x4*)(XAT_SRC(db + 10) + 8); }
;         f32x16 o = {};
; #pragma unroll
;         for (int kb = 0; kb < 8; ++kb)
; #pragma unroll
;             for (int s = 0; s < 2; ++s) { const bf16x8 vf = *(const XLAS bf16x8*)(buf + vro + kb * 64 + s * 32); o = __builtin_amdgcn_mfma_f32_32x32x16_bf16(vf, __builtin_bit_cast(bf16x8, pw[kb][s]), o, 0, 0, 0); }
; #pragma unroll
;         for (int g4 = 0; g4 < 4; ++g4) { u32x2 w; w.x = cvtpk(o[4 * g4] * rl, o[4 * g4 + 1] * rl); w.y = cvtpk(o[4 * g4 + 2] * rl, o[4 * g4 + 3] * rl);
;             *(XLAS u32x2*)(xs + r32 * 144 + ((db & 1) * 32 + 8 * g4 + 4 * hi) * 2) = w; }
;         if (db & 1) {
; #pragma unroll
;             for (int i = 0; i < 4; ++i) { const u32x4 v = *(const XLAS u32x4*)(xs + (8 * i + (lane >> 3)) * 144 + (lane & 7) * 16); *(u32x4*)(obase + (size_t)(8 * i) * 1024 + (db >> 1) * 64) = v; }
;         }
	ds_read_b128 v[140:143], v99
	ds_read_b128 v[144:147], v99 offset:32
	ds_read_b128 v[148:151], v99 offset:64
	ds_read_b128 v[152:155], v99 offset:96
	ds_read_b128 v[156:159], v99 offset:128
	ds_read_b128 v[160:163], v99 offset:160
	ds_read_b128 v[164:167], v99 offset:192
	ds_read_b128 v[168:171], v99 offset:224
	s_waitcnt lgkmcnt(7)
	v_mfma_f32_32x32x16_bf16 v[2:17], v[140:143], v[130:133], 0
	ds_read_b128 v[140:143], v99 offset:256
	s_waitcnt lgkmcnt(7)
	v_mfma_f32_32x32x16_bf16 v[2:17], v[144:147], v[134:137], v[2:17]
	ds_read_b128 v[144:147], v99 offset:288
	s_waitcnt lgkmcnt(7)
	v_mfma_f32_32x32x16_bf16 v[2:17], v[148:151], v[34:37], v[2:17]
	ds_read_b128 v[148:151], v99 offset:320
	s_waitcnt lgkmcnt(7)
	v_mfma_f32_32x32x16_bf16 v[2:17], v[152:155], v[38:41], v[2:17]
	ds_read_b128 v[152:155], v99 offset:352
	s_waitcnt lgkmcnt(7)
	v_mfma_f32_32x32x16_bf16 v[2:17], v[156:159], v[42:45], v[2:17]
	ds_read_b128 v[156:159], v99 offset:384
	s_waitcnt lgkmcnt(7)
	v_mfma_f32_32x32x16_bf16 v[2:17], v[160:163], v[46:49], v[2:17]
	ds_read_b128 v[160:163], v99 offset:416
	s_waitcnt lgkmcnt(7)
	v_mfma_f32_32x32x16_bf16 v[2:17], v[164:167], v[50:53], v[2:17]
	ds_read_b128 v[164:167], v99 offset:448
	s_waitcnt lgkmcnt(7)
	v_mfma_f32_32x32x16_bf16 v[2:17], v[168:171], v[54:57], v[2:17]
	ds_read_b128 v[168:171], v99 offset:480
	s_waitcnt lgkmcnt(7)
	v_mfma_f32_32x32x16_bf16 v[2:17], v[140:143], v[58:61], v[2:17]
	s_waitcnt lgkmcnt(6)
	v_mfma_f32_32x32x16_bf16 v[2:17], v[144:147], v[62:65], v[2:17]
	s_waitcnt lgkmcnt(5)
	v_mfma_f32_32x32x16_bf16 v[2:17], v[148:151], v[66:69], v[2:17]
	s_waitcnt lgkmcnt(4)
	v_mfma_f32_32x32x16_bf16 v[2:17], v[152:155], v[70:73], v[2:17]
	s_waitcnt lgkmcnt(3)
	v_mfma_f32_32x32x16_bf16 v[2:17], v[156:159], v[74:77], v[2:17]
	s_waitcnt lgkmcnt(2)
	v_mfma_f32_32x32x16_bf16 v[2:17], v[160:163], v[78:81], v[2:17]
	s_waitcnt lgkmcnt(1)
	v_mfma_f32_32x32x16_bf16 v[2:17], v[164:167], v[86:89], v[2:17]
	s_waitcnt lgkmcnt(0)
	v_mfma_f32_32x32x16_bf16 v[2:17], v[168:171], v[82:85], v[2:17]
	s_nop 11
	v_pk_mul_f32 v[2:3], v[98:99], v[2:3] op_sel_hi:[0,1]
	v_pk_mul_f32 v[4:5], v[98:99], v[4:5] op_sel_hi:[0,1]
	v_pk_mul_f32 v[6:7], v[98:99], v[6:7] op_sel_hi:[0,1]
	v_pk_mul_f32 v[8:9], v[98:99], v[8:9] op_sel_hi:[0,1]
	v_pk_mul_f32 v[10:11], v[98:99], v[10:11] op_sel_hi:[0,1]
	v_pk_mul_f32 v[12:13], v[98:99], v[12:13] op_sel_hi:[0,1]
	v_pk_mul_f32 v[14:15], v[98:99], v[14:15] op_sel_hi:[0,1]
	v_pk_mul_f32 v[16:17], v[98:99], v[16:17] op_sel_hi:[0,1]
	v_cvt_pk_bf16_f32 v2, v2, v3
	v_cvt_pk_bf16_f32 v3, v4, v5
	v_cvt_pk_bf16_f32 v4, v6, v7
	v_cvt_pk_bf16_f32 v5, v8, v9
	v_cvt_pk_bf16_f32 v6, v10, v11
	v_cvt_pk_bf16_f32 v7, v12, v13
	v_cvt_pk_bf16_f32 v8, v14, v15
	v_cvt_pk_bf16_f32 v9, v16, v17
	ds_write2_b64 v100, v[2:3], v[4:5] offset1:2
	ds_write2_b64 v100, v[6:7], v[8:9] offset0:4 offset1:6
	s_waitcnt vmcnt(5)
	ds_write_b128 v214, v[90:93] offset:16896
	s_waitcnt vmcnt(4)
	ds_write_b128 v214, v[94:97] offset:16912
	s_waitcnt lgkmcnt(0)
	s_barrier
	ds_read_b128 v[140:143], v99 offset:16896
	ds_read_b128 v[144:147], v99 offset:16928
	ds_read_b128 v[148:151], v99 offset:16960
	ds_read_b128 v[152:155], v99 offset:16992
	ds_read_b128 v[156:159], v99 offset:17024
	ds_read_b128 v[160:163], v99 offset:17056
	ds_read_b128 v[164:167], v99 offset:17088
	ds_read_b128 v[168:171], v99 offset:17120
	s_waitcnt lgkmcnt(7)
	v_mfma_f32_32x32x16_bf16 v[2:17], v[140:143], v[130:133], 0
	ds_read_b128 v[140:143], v99 offset:17152
	s_waitcnt lgkmcnt(7)
	v_mfma_f32_32x32x16_bf16 v[2:17], v[144:147], v[134:137], v[2:17]
	ds_read_b128 v[144:147], v99 offset:17184
	s_waitcnt lgkmcnt(7)
	v_mfma_f32_32x32x16_bf16 v[2:17], v[148:151], v[34:37], v[2:17]
	ds_read_b128 v[148:151], v99 offset:17216
	s_waitcnt lgkmcnt(7)
	v_mfma_f32_32x32x16_bf16 v[2:17], v[152:155], v[38:41], v[2:17]
	ds_read_b128 v[152:155], v99 offset:17248
	s_waitcnt lgkmcnt(7)
	v_mfma_f32_32x32x16_bf16 v[2:17], v[156:159], v[42:45], v[2:17]
	ds_read_b128 v[156:159], v99 offset:17280
	s_waitcnt lgkmcnt(7)
	v_mfma_f32_32x32x16_bf16 v[2:17], v[160:163], v[46:49], v[2:17]
	ds_read_b128 v[160:163], v99 offset:17312
	s_waitcnt lgkmcnt(7)
	v_mfma_f32_32x32x16_bf16 v[2:17], v[164:167], v[50:53], v[2:17]
	ds_read_b128 v[164:167], v99 offset:17344
	s_waitcnt lgkmcnt(7)
	v_mfma_f32_32x32x16_bf16 v[2:17], v[168:171], v[54:57], v[2:17]
	ds_read_b128 v[168:171], v99 offset:17376
	s_waitcnt lgkmcnt(7)
	v_mfma_f32_32x32x16_bf16 v[2:17], v[140:143], v[58:61], v[2:17]
	s_waitcnt lgkmcnt(6)
	v_mfma_f32_32x32x16_bf16 v[2:17], v[144:147], v[62:65], v[2:17]
	s_waitcnt lgkmcnt(5)
	v_mfma_f32_32x32x16_bf16 v[2:17], v[148:151], v[66:69], v[2:17]
	s_waitcnt lgkmcnt(4)
	v_mfma_f32_32x32x16_bf16 v[2:17], v[152:155], v[70:73], v[2:17]
	s_waitcnt lgkmcnt(3)
	v_mfma_f32_32x32x16_bf16 v[2:17], v[156:159], v[74:77], v[2:17]
	s_waitcnt lgkmcnt(2)
	v_mfma_f32_32x32x16_bf16 v[2:17], v[160:163], v[78:81], v[2:17]
	s_waitcnt lgkmcnt(1)
	v_mfma_f32_32x32x16_bf16 v[2:17], v[164:167], v[86:89], v[2:17]
	s_waitcnt lgkmcnt(0)
	v_mfma_f32_32x32x16_bf16 v[2:17], v[168:171], v[82:85], v[2:17]
	s_nop 11
	v_pk_mul_f32 v[2:3], v[98:99], v[2:3] op_sel_hi:[0,1]
	v_pk_mul_f32 v[4:5], v[98:99], v[4:5] op_sel_hi:[0,1]
	v_pk_mul_f32 v[6:7], v[98:99], v[6:7] op_sel_hi:[0,1]
	v_pk_mul_f32 v[8:9], v[98:99], v[8:9] op_sel_hi:[0,1]
	v_pk_mul_f32 v[10:11], v[98:99], v[10:11] op_sel_hi:[0,1]
	v_pk_mul_f32 v[12:13], v[98:99], v[12:13] op_sel_hi:[0,1]
	v_pk_mul_f32 v[14:15], v[98:99], v[14:15] op_sel_hi:[0,1]
	v_pk_mul_f32 v[16:17], v[98:99], v[16:17] op_sel_hi:[0,1]
	v_cvt_pk_bf16_f32 v2, v2, v3
	v_cvt_pk_bf16_f32 v3, v4, v5
	v_cvt_pk_bf16_f32 v4, v6, v7
	v_cvt_pk_bf16_f32 v5, v8, v9
	v_cvt_pk_bf16_f32 v6, v10, v11
	v_cvt_pk_bf16_f32 v7, v12, v13
	v_cvt_pk_bf16_f32 v8, v14, v15
	v_cvt_pk_bf16_f32 v9, v16, v17
	ds_write2_b64 v100, v[2:3], v[4:5] offset0:8 offset1:10
	ds_write2_b64 v100, v[6:7], v[8:9] offset0:12 offset1:14
	ds_read_b128 v[2:5], v0 offset:34816
	ds_read_b128 v[6:9], v0 offset:35968
	ds_read_b128 v[10:13], v0 offset:37120
	ds_read_b128 v[14:17], v0 offset:38272
	s_waitcnt lgkmcnt(3)
	global_store_dwordx4 v[26:27], v[2:5], off offset:384
	s_waitcnt lgkmcnt(2)
	global_store_dwordx4 v[28:29], v[6:9], off offset:384
	s_waitcnt lgkmcnt(1)
	global_store_dwordx4 v[30:31], v[10:13], off offset:384
	s_waitcnt lgkmcnt(0)
	global_store_dwordx4 v[32:33], v[14:17], off offset:384
	s_branch .LBB0_585
